# attention first-chunk loads hoisted to unit top; EpiRes epilogues prefetch all residual-source lines up front (dummy loads)
# baseline (speedup 1.0000x reference)
.LBB0_598:
	s_waitcnt lgkmcnt(0)
	v_pk_add_f32 v[164:165], v[164:165], 1.0 op_sel_hi:[1,0]
	v_pk_add_f32 v[166:167], v[166:167], 1.0 op_sel_hi:[1,0]
	v_pk_mul_f32 v[160:161], v[160:161], v[164:165]
	v_pk_add_f32 v[158:159], v[158:159], 1.0 op_sel_hi:[1,0]
	v_pk_add_f32 v[164:165], v[156:157], 1.0 op_sel_hi:[1,0]
	v_pk_add_f32 v[150:151], v[150:151], 1.0 op_sel_hi:[1,0]
	v_pk_add_f32 v[148:149], v[148:149], 1.0 op_sel_hi:[1,0]
	v_pk_mul_f32 v[162:163], v[162:163], v[166:167]
	v_pk_mul_f32 v[156:157], v[154:155], v[158:159]
	v_pk_mul_f32 v[158:159], v[152:153], v[164:165]
	v_pk_mul_f32 v[164:165], v[146:147], v[150:151]
	v_pk_mul_f32 v[166:167], v[144:145], v[148:149]
	ds_read_b128 v[144:147], v202 offset:2576
	ds_read_b128 v[148:151], v202 offset:3600
	v_lshl_add_u32 v206, s36, 8, v216
	v_readlane_b32 s72, v243, 5
	s_cmpk_lt_i32 s36, 0x100
	v_readlane_b32 s73, v243, 6
	s_waitcnt lgkmcnt(0)
	v_pk_add_f32 v[148:149], v[148:149], 1.0 op_sel_hi:[1,0]
	v_lshl_or_b32 v202, s2, 8, v219
	v_ashrrev_i32_e32 v207, 31, v206
	v_pk_mul_f32 v[152:153], v[144:145], v[148:149]
	s_cselect_b32 s1, s73, s64
	s_cselect_b32 s0, s72, s63
	v_ashrrev_i32_e32 v203, 31, v202
	v_lshlrev_b64 v[144:145], 12, v[206:207]
	v_lshl_add_u64 v[144:145], s[0:1], 0, v[144:145]
	v_lshlrev_b64 v[204:205], 2, v[202:203]
	v_pk_add_f32 v[150:151], v[150:151], 1.0 op_sel_hi:[1,0]
	v_lshl_add_u64 v[148:149], v[144:145], 0, v[204:205]
	v_pk_mul_f32 v[154:155], v[146:147], v[150:151]
	global_load_dwordx4 v[210:213], v[148:149], off offset:16
	global_load_dwordx4 v[228:231], v[148:149], off
	global_load_dwordx4 v[144:147], v[148:149], off offset:528
	s_mov_b32 s98, 0x10000
	s_mov_b32 s99, 0
	s_mov_b32 s100, 0x50000
	s_mov_b32 s101, 0
	v_lshl_add_u64 v[248:249], v[148:149], 0, s[98:99]
	global_load_dwordx4 v[244:247], v[248:249], off
	global_load_dwordx4 v[244:247], v[248:249], off offset:512
	v_lshl_add_u64 v[248:249], v[248:249], 0, s[98:99]
	global_load_dwordx4 v[244:247], v[248:249], off
	global_load_dwordx4 v[244:247], v[248:249], off offset:512
	v_lshl_add_u64 v[248:249], v[248:249], 0, s[98:99]
	global_load_dwordx4 v[244:247], v[248:249], off
	global_load_dwordx4 v[244:247], v[248:249], off offset:512
	v_lshl_add_u64 v[248:249], v[248:249], 0, s[100:101]
	global_load_dwordx4 v[244:247], v[248:249], off
	global_load_dwordx4 v[244:247], v[248:249], off offset:512
	v_lshl_add_u64 v[248:249], v[248:249], 0, s[98:99]
	global_load_dwordx4 v[244:247], v[248:249], off
	global_load_dwordx4 v[244:247], v[248:249], off offset:512
	v_lshl_add_u64 v[248:249], v[248:249], 0, s[98:99]
	global_load_dwordx4 v[244:247], v[248:249], off
	global_load_dwordx4 v[244:247], v[248:249], off offset:512
	v_lshl_add_u64 v[248:249], v[248:249], 0, s[98:99]
	global_load_dwordx4 v[244:247], v[248:249], off
	global_load_dwordx4 v[244:247], v[248:249], off offset:512
	s_nop 0
	global_load_dwordx4 v[148:151], v[148:149], off offset:512
	v_and_b32_e32 v209, 64, v224
	v_xor_b32_e32 v208, 16, v224
	v_add_u32_e32 v209, 64, v209
	v_cmp_lt_i32_e32 vcc, v208, v209
	v_readlane_b32 s74, v243, 7
	v_readlane_b32 s75, v243, 8
	v_cndmask_b32_e32 v208, v224, v208, vcc
	v_lshlrev_b32_e32 v226, 2, v208
	v_xor_b32_e32 v208, 32, v224
	v_cmp_lt_i32_e32 vcc, v208, v209
	v_readlane_b32 s76, v243, 9
	v_readlane_b32 s77, v243, 10
	v_readlane_b32 s78, v243, 11
	v_readlane_b32 s79, v243, 12
	v_readlane_b32 s80, v243, 13
	v_readlane_b32 s81, v243, 14
	v_readlane_b32 s82, v243, 15
	v_readlane_b32 s83, v243, 16
	v_readlane_b32 s84, v243, 17
	v_readlane_b32 s85, v243, 18
	v_readlane_b32 s86, v243, 19
	v_readlane_b32 s87, v243, 20
	v_cndmask_b32_e32 v208, v224, v208, vcc
	v_readlane_b32 s72, v243, 21
	v_lshlrev_b32_e32 v225, 2, v208
	v_lshlrev_b64 v[208:209], 10, v[206:207]
	v_readlane_b32 s87, v243, 36
	v_readlane_b32 s27, v242, 24
	v_lshl_add_u64 v[232:233], v[208:209], 0, v[202:203]
	v_or_b32_e32 v208, 16, v206
	v_readlane_b32 s86, v243, 35
	s_cselect_b32 s37, s87, s27
	v_readlane_b32 s27, v242, 23
	v_ashrrev_i32_e32 v209, 31, v208
	s_cselect_b32 s36, s86, s27
	v_lshl_add_u64 v[204:205], s[0:1], 0, v[204:205]
	v_lshlrev_b64 v[214:215], 12, v[208:209]
	v_lshl_add_u64 v[214:215], v[204:205], 0, v[214:215]
	s_lshl_b32 s0, s2, 2
	s_ashr_i32 s1, s0, 31
	v_readlane_b32 s73, v243, 22
	v_readlane_b32 s74, v243, 23
	v_readlane_b32 s75, v243, 24
	v_readlane_b32 s76, v243, 25
	v_readlane_b32 s77, v243, 26
	v_readlane_b32 s78, v243, 27
	v_readlane_b32 s79, v243, 28
	v_readlane_b32 s80, v243, 29
	v_readlane_b32 s81, v243, 30
	v_readlane_b32 s82, v243, 31
	v_readlane_b32 s83, v243, 32
	v_readlane_b32 s84, v243, 33
	v_readlane_b32 s85, v243, 34
	s_waitcnt vmcnt(0)
	v_pk_fma_f32 v[138:139], v[138:139], v[58:59], v[212:213]
	v_pk_fma_f32 v[142:143], v[142:143], v[50:51], v[230:231]
	v_pk_fma_f32 v[140:141], v[140:141], v[48:49], v[228:229]
	v_pk_fma_f32 v[136:137], v[136:137], v[56:57], v[210:211]
	v_pk_add_f32 v[234:235], v[188:189], v[142:143]
	v_pk_add_f32 v[236:237], v[186:187], v[140:141]
	v_pk_add_f32 v[238:239], v[198:199], v[138:139]
	v_pk_add_f32 v[240:241], v[190:191], v[136:137]
	v_lshlrev_b64 v[210:211], 1, v[232:233]
	v_cvt_pk_bf16_f32 v228, v236, v237
	v_cvt_pk_bf16_f32 v229, v234, v235
	v_cvt_pk_bf16_f32 v230, v240, v241
	v_cvt_pk_bf16_f32 v231, v238, v239
	v_lshl_add_u64 v[212:213], s[36:37], 0, v[210:211]
	global_load_dwordx4 v[136:139], v[214:215], off offset:16
	global_load_dwordx4 v[140:143], v[214:215], off
	v_mul_f32_e32 v227, v237, v237
	global_store_dwordx4 v[212:213], v[228:231], off
	v_fmac_f32_e32 v227, v236, v236
	v_pk_mul_f32 v[232:233], v[156:157], v[238:239]
	v_mul_f32_e32 v228, v235, v235
	v_fmac_f32_e32 v228, v234, v234
	v_add_f32_e32 v227, v227, v228
	v_mul_f32_e32 v228, v241, v241
	v_mul_f32_e32 v229, v239, v239
	v_fmac_f32_e32 v228, v240, v240
	v_fmac_f32_e32 v229, v238, v238
	v_add_f32_e32 v228, v228, v229
	v_add_f32_e32 v227, v227, v228
	v_pk_mul_f32 v[230:231], v[164:165], v[234:235]
	v_pk_mul_f32 v[228:229], v[166:167], v[236:237]
	v_pk_mul_f32 v[234:235], v[158:159], v[240:241]
	v_cvt_pk_bf16_f32 v228, v228, v229
	v_cvt_pk_bf16_f32 v229, v230, v231
	v_cvt_pk_bf16_f32 v230, v234, v235
	v_cvt_pk_bf16_f32 v231, v232, v233
	v_lshl_add_u64 v[232:233], s[8:9], 0, v[210:211]
	global_store_dwordx4 v[232:233], v[228:231], off
	v_pk_fma_f32 v[134:135], v[134:135], v[54:55], v[150:151]
	v_pk_fma_f32 v[132:133], v[132:133], v[52:53], v[148:149]
	v_pk_fma_f32 v[130:131], v[130:131], v[62:63], v[146:147]
	v_pk_fma_f32 v[128:129], v[128:129], v[60:61], v[144:145]
	v_pk_add_f32 v[148:149], v[194:195], v[134:135]
	v_pk_add_f32 v[150:151], v[192:193], v[132:133]
	v_pk_add_f32 v[228:229], v[200:201], v[130:131]
	v_pk_add_f32 v[230:231], v[196:197], v[128:129]
	global_load_dwordx4 v[128:131], v[214:215], off offset:528
	global_load_dwordx4 v[132:135], v[214:215], off offset:512
	v_cvt_pk_bf16_f32 v144, v150, v151
	v_cvt_pk_bf16_f32 v145, v148, v149
	v_cvt_pk_bf16_f32 v146, v230, v231
	v_cvt_pk_bf16_f32 v147, v228, v229
	global_store_dwordx4 v[212:213], v[144:147], off offset:256
	v_or_b32_e32 v210, 0x100, v210
	s_nop 0
	v_mul_f32_e32 v144, v151, v151
	v_mul_f32_e32 v145, v149, v149
	v_fmac_f32_e32 v144, v150, v150
	v_fmac_f32_e32 v145, v148, v148
	v_add_f32_e32 v144, v144, v145
	v_mul_f32_e32 v145, v231, v231
	v_mul_f32_e32 v146, v229, v229
	v_fmac_f32_e32 v145, v230, v230
	v_fmac_f32_e32 v146, v228, v228
	v_add_f32_e32 v144, v227, v144
	v_add_f32_e32 v145, v145, v146
	v_add_f32_e32 v212, v144, v145
	v_pk_mul_f32 v[146:147], v[162:163], v[148:149]
	v_pk_mul_f32 v[144:145], v[160:161], v[150:151]
	v_pk_mul_f32 v[148:149], v[154:155], v[228:229]
	v_pk_mul_f32 v[150:151], v[152:153], v[230:231]
	v_cvt_pk_bf16_f32 v144, v144, v145
	v_cvt_pk_bf16_f32 v145, v146, v147
	v_cvt_pk_bf16_f32 v146, v150, v151
	v_cvt_pk_bf16_f32 v147, v148, v149
	v_lshl_add_u64 v[148:149], s[8:9], 0, v[210:211]
	global_store_dwordx4 v[148:149], v[144:147], off
	ds_bpermute_b32 v144, v226, v212
	s_waitcnt lgkmcnt(0)
	v_add_f32_e32 v144, v212, v144
	ds_bpermute_b32 v145, v225, v144
	s_and_saveexec_b64 s[38:39], s[4:5]
	s_cbranch_execz .LBB0_600
	v_lshlrev_b64 v[146:147], 6, v[206:207]
	v_lshl_add_u64 v[146:147], s[12:13], 0, v[146:147]
	v_lshl_add_u64 v[146:147], s[0:1], 2, v[146:147]
	s_lshl_b32 s2, s65, 2
	v_lshl_add_u64 v[146:147], v[146:147], 0, s[2:3]
	s_waitcnt lgkmcnt(0)
	v_add_f32_e32 v144, v144, v145
	global_store_dword v[146:147], v144, off

.LBB0_876:
	ds_read_b128 v[68:71], v194
	ds_read_b128 v[76:79], v194 offset:1024
	ds_read_b128 v[136:139], v194 offset:2048
	ds_read_b128 v[140:143], v194 offset:3072
	s_add_u32 s40, s0, 0xfff00080
	s_addc_u32 s41, s1, -1
	s_cmp_eq_u32 s67, 60
	s_cselect_b32 s45, s29, s41
	s_cselect_b32 s44, s43, s40
	s_cselect_b32 s41, s27, s47
	s_cselect_b32 s40, s48, s46
	v_lshl_add_u64 v[206:207], s[0:1], 0, v[152:153]
	s_add_i32 m0, s49, 0xc000
	ds_read_b128 v[160:163], v195
	ds_read_b128 v[164:167], v195 offset:1024
	ds_read_b128 v[170:173], v195 offset:2048
	ds_read_b128 v[174:177], v195 offset:3072
	ds_read_b128 v[178:181], v195 offset:4096
	ds_read_b128 v[182:185], v195 offset:5120
	ds_read_b128 v[198:201], v195 offset:6144
	ds_read_b128 v[202:205], v195 offset:7168
	global_load_lds_dwordx4 v[206:207], off
	v_lshl_add_u64 v[206:207], s[0:1], 0, v[154:155]
	s_add_i32 m0, s49, 0xe000
	s_nop 0
	global_load_lds_dwordx4 v[206:207], off
	s_waitcnt lgkmcnt(8)
	s_barrier
	s_waitcnt lgkmcnt(0)
	s_setprio 1
	s_waitcnt lgkmcnt(0)
	v_mfma_f32_16x16x32_bf16 v[92:95], v[68:71], v[160:163], v[92:95]
	v_mfma_f32_16x16x32_bf16 v[88:91], v[136:139], v[160:163], v[88:91]
	v_mfma_f32_16x16x32_bf16 v[124:127], v[68:71], v[170:173], v[124:127]
	v_mfma_f32_16x16x32_bf16 v[120:123], v[136:139], v[170:173], v[120:123]
	v_mfma_f32_16x16x32_bf16 v[108:111], v[68:71], v[178:181], v[108:111]
	v_mfma_f32_16x16x32_bf16 v[104:107], v[136:139], v[178:181], v[104:107]
	v_mfma_f32_16x16x32_bf16 v[84:87], v[68:71], v[198:201], v[84:87]
	v_mfma_f32_16x16x32_bf16 v[80:83], v[136:139], v[198:201], v[80:83]
	v_mfma_f32_16x16x32_bf16 v[92:95], v[76:79], v[164:167], v[92:95]
	v_mfma_f32_16x16x32_bf16 v[88:91], v[140:143], v[164:167], v[88:91]
	v_mfma_f32_16x16x32_bf16 v[124:127], v[76:79], v[174:177], v[124:127]
	v_mfma_f32_16x16x32_bf16 v[120:123], v[140:143], v[174:177], v[120:123]
	v_mfma_f32_16x16x32_bf16 v[108:111], v[76:79], v[182:185], v[108:111]
	v_mfma_f32_16x16x32_bf16 v[104:107], v[140:143], v[182:185], v[104:107]
	v_mfma_f32_16x16x32_bf16 v[84:87], v[76:79], v[202:205], v[84:87]
	v_mfma_f32_16x16x32_bf16 v[80:83], v[140:143], v[202:205], v[80:83]
	s_setprio 0
	s_barrier
	s_add_i32 s68, s64, s52
	v_lshl_add_u64 v[222:223], s[40:41], 0, v[146:147]
	s_mov_b32 m0, s68
	ds_read_b128 v[206:209], v196
	ds_read_b128 v[210:213], v196 offset:1024
	ds_read_b128 v[214:217], v196 offset:2048
	ds_read_b128 v[218:221], v196 offset:3072
	global_load_lds_dwordx4 v[222:223], off
	v_lshl_add_u64 v[224:225], s[40:41], 0, v[150:151]
	s_add_i32 m0, s68, 0x2000
	s_nop 0
	global_load_lds_dwordx4 v[224:225], off
	s_barrier
	s_waitcnt lgkmcnt(0)
	s_setprio 1
	s_waitcnt lgkmcnt(0)
	v_mfma_f32_16x16x32_bf16 v[132:135], v[206:209], v[160:163], v[132:135]
	v_mfma_f32_16x16x32_bf16 v[128:131], v[214:217], v[160:163], v[128:131]
	v_mfma_f32_16x16x32_bf16 v[116:119], v[206:209], v[170:173], v[116:119]
	v_mfma_f32_16x16x32_bf16 v[112:115], v[214:217], v[170:173], v[112:115]
	v_mfma_f32_16x16x32_bf16 v[100:103], v[206:209], v[178:181], v[100:103]
	v_mfma_f32_16x16x32_bf16 v[96:99], v[214:217], v[178:181], v[96:99]
	v_mfma_f32_16x16x32_bf16 v[72:75], v[206:209], v[198:201], v[72:75]
	v_mfma_f32_16x16x32_bf16 v[64:67], v[214:217], v[198:201], v[64:67]
	v_mfma_f32_16x16x32_bf16 v[132:135], v[210:213], v[164:167], v[132:135]
	v_mfma_f32_16x16x32_bf16 v[128:131], v[218:221], v[164:167], v[128:131]
	v_mfma_f32_16x16x32_bf16 v[116:119], v[210:213], v[174:177], v[116:119]
	v_mfma_f32_16x16x32_bf16 v[112:115], v[218:221], v[174:177], v[112:115]
	v_mfma_f32_16x16x32_bf16 v[100:103], v[210:213], v[182:185], v[100:103]
	v_mfma_f32_16x16x32_bf16 v[96:99], v[218:221], v[182:185], v[96:99]
	v_mfma_f32_16x16x32_bf16 v[72:75], v[210:213], v[202:205], v[72:75]
	v_mfma_f32_16x16x32_bf16 v[64:67], v[218:221], v[202:205], v[64:67]
	s_setprio 0
	s_mov_b32 m0, s49
	v_lshl_add_u64 v[226:227], s[44:45], 0, v[144:145]
	s_barrier
	ds_read_b128 v[160:163], v195 offset:16384
	ds_read_b128 v[164:167], v195 offset:17408
	ds_read_b128 v[170:173], v195 offset:18432
	ds_read_b128 v[174:177], v195 offset:19456
	ds_read_b128 v[178:181], v195 offset:20480
	ds_read_b128 v[182:185], v195 offset:21504
	ds_read_b128 v[198:201], v195 offset:22528
	ds_read_b128 v[202:205], v195 offset:23552
	global_load_lds_dwordx4 v[226:227], off
	v_lshl_add_u64 v[228:229], s[44:45], 0, v[148:149]
	s_mov_b32 m0, s53
	s_nop 0
	global_load_lds_dwordx4 v[228:229], off
	s_barrier
	s_waitcnt lgkmcnt(0)
	s_setprio 1
	s_waitcnt lgkmcnt(0)
	v_mfma_f32_16x16x32_bf16 v[60:63], v[68:71], v[160:163], v[60:63]
	v_mfma_f32_16x16x32_bf16 v[56:59], v[136:139], v[160:163], v[56:59]
	v_mfma_f32_16x16x32_bf16 v[44:47], v[68:71], v[170:173], v[44:47]
	v_mfma_f32_16x16x32_bf16 v[40:43], v[136:139], v[170:173], v[40:43]
	v_mfma_f32_16x16x32_bf16 v[28:31], v[68:71], v[178:181], v[28:31]
	v_mfma_f32_16x16x32_bf16 v[24:27], v[136:139], v[178:181], v[24:27]
	v_mfma_f32_16x16x32_bf16 v[8:11], v[68:71], v[198:201], v[8:11]
	v_mfma_f32_16x16x32_bf16 v[12:15], v[136:139], v[198:201], v[12:15]
	v_mfma_f32_16x16x32_bf16 v[60:63], v[76:79], v[164:167], v[60:63]
	v_mfma_f32_16x16x32_bf16 v[56:59], v[140:143], v[164:167], v[56:59]
	v_mfma_f32_16x16x32_bf16 v[44:47], v[76:79], v[174:177], v[44:47]
	v_mfma_f32_16x16x32_bf16 v[40:43], v[140:143], v[174:177], v[40:43]
	v_mfma_f32_16x16x32_bf16 v[28:31], v[76:79], v[182:185], v[28:31]
	v_mfma_f32_16x16x32_bf16 v[24:27], v[140:143], v[182:185], v[24:27]
	v_mfma_f32_16x16x32_bf16 v[8:11], v[76:79], v[202:205], v[8:11]
	v_mfma_f32_16x16x32_bf16 v[12:15], v[140:143], v[202:205], v[12:15]
	s_setprio 0
	s_barrier
	s_add_u32 s68, s40, 0x100000
	s_addc_u32 s69, s41, 0
	s_add_i32 s70, s65, s52
	v_lshl_add_u64 v[68:69], s[68:69], 0, v[146:147]
	s_mov_b32 m0, s70
	s_nop 0
	global_load_lds_dwordx4 v[68:69], off
	v_lshl_add_u64 v[68:69], s[68:69], 0, v[150:151]
	s_add_i32 m0, s70, 0x2000
	s_nop 0
	global_load_lds_dwordx4 v[68:69], off
	s_waitcnt vmcnt(6)
	s_barrier
	s_setprio 1
	v_mfma_f32_16x16x32_bf16 v[52:55], v[206:209], v[160:163], v[52:55]
	v_mfma_f32_16x16x32_bf16 v[48:51], v[214:217], v[160:163], v[48:51]
	v_mfma_f32_16x16x32_bf16 v[36:39], v[206:209], v[170:173], v[36:39]
	v_mfma_f32_16x16x32_bf16 v[32:35], v[214:217], v[170:173], v[32:35]
	v_mfma_f32_16x16x32_bf16 v[20:23], v[206:209], v[178:181], v[20:23]
	v_mfma_f32_16x16x32_bf16 v[16:19], v[214:217], v[178:181], v[16:19]
	v_mfma_f32_16x16x32_bf16 v[0:3], v[206:209], v[198:201], v[0:3]
	v_mfma_f32_16x16x32_bf16 v[4:7], v[214:217], v[198:201], v[4:7]
	v_mfma_f32_16x16x32_bf16 v[52:55], v[210:213], v[164:167], v[52:55]
	v_mfma_f32_16x16x32_bf16 v[48:51], v[218:221], v[164:167], v[48:51]
	v_mfma_f32_16x16x32_bf16 v[36:39], v[210:213], v[174:177], v[36:39]
	v_mfma_f32_16x16x32_bf16 v[32:35], v[218:221], v[174:177], v[32:35]
	v_mfma_f32_16x16x32_bf16 v[20:23], v[210:213], v[182:185], v[20:23]
	v_mfma_f32_16x16x32_bf16 v[16:19], v[218:221], v[182:185], v[16:19]
	v_mfma_f32_16x16x32_bf16 v[0:3], v[210:213], v[202:205], v[0:3]
	v_mfma_f32_16x16x32_bf16 v[4:7], v[218:221], v[202:205], v[4:7]
	s_setprio 0
	s_add_i32 s68, 0, 0x18000
	v_add_u32_e32 v140, s68, v189
	s_barrier
	ds_read_b128 v[68:71], v140
	ds_read_b128 v[76:79], v140 offset:1024
	ds_read_b128 v[136:139], v140 offset:2048
	ds_read_b128 v[140:143], v140 offset:3072
	s_add_u32 s44, s44, 0x100000
	s_addc_u32 s45, s45, 0
	s_mov_b32 m0, s54
	v_lshl_add_u64 v[206:207], s[44:45], 0, v[144:145]
	ds_read_b128 v[160:163], v195 offset:32768
	ds_read_b128 v[164:167], v195 offset:33792
	ds_read_b128 v[170:173], v195 offset:34816
	ds_read_b128 v[174:177], v195 offset:35840
	ds_read_b128 v[178:181], v195 offset:36864
	ds_read_b128 v[182:185], v195 offset:37888
	ds_read_b128 v[198:201], v195 offset:38912
	ds_read_b128 v[202:205], v195 offset:39936
	global_load_lds_dwordx4 v[206:207], off
	v_lshl_add_u64 v[206:207], s[44:45], 0, v[148:149]
	s_mov_b32 m0, s55
	s_nop 0
	global_load_lds_dwordx4 v[206:207], off
	s_waitcnt lgkmcnt(8)
	s_barrier
	s_waitcnt lgkmcnt(0)
	s_setprio 1
	s_waitcnt lgkmcnt(0)
	v_mfma_f32_16x16x32_bf16 v[92:95], v[68:71], v[160:163], v[92:95]
	v_mfma_f32_16x16x32_bf16 v[88:91], v[136:139], v[160:163], v[88:91]
	v_mfma_f32_16x16x32_bf16 v[124:127], v[68:71], v[170:173], v[124:127]
	v_mfma_f32_16x16x32_bf16 v[120:123], v[136:139], v[170:173], v[120:123]
	v_mfma_f32_16x16x32_bf16 v[108:111], v[68:71], v[178:181], v[108:111]
	v_mfma_f32_16x16x32_bf16 v[104:107], v[136:139], v[178:181], v[104:107]
	v_mfma_f32_16x16x32_bf16 v[84:87], v[68:71], v[198:201], v[84:87]
	v_mfma_f32_16x16x32_bf16 v[80:83], v[136:139], v[198:201], v[80:83]
	v_mfma_f32_16x16x32_bf16 v[92:95], v[76:79], v[164:167], v[92:95]
	v_mfma_f32_16x16x32_bf16 v[88:91], v[140:143], v[164:167], v[88:91]
	v_mfma_f32_16x16x32_bf16 v[124:127], v[76:79], v[174:177], v[124:127]
	v_mfma_f32_16x16x32_bf16 v[120:123], v[140:143], v[174:177], v[120:123]
	v_mfma_f32_16x16x32_bf16 v[108:111], v[76:79], v[182:185], v[108:111]
	v_mfma_f32_16x16x32_bf16 v[104:107], v[140:143], v[182:185], v[104:107]
	v_mfma_f32_16x16x32_bf16 v[84:87], v[76:79], v[202:205], v[84:87]
	v_mfma_f32_16x16x32_bf16 v[80:83], v[140:143], v[202:205], v[80:83]
	s_setprio 0
	s_barrier
	s_add_i32 s44, 0, 0x1c000
	s_add_i32 s45, s68, s52
	v_add_u32_e32 v218, s44, v189
	v_lshl_add_u64 v[222:223], v[222:223], 0, s[20:21]
	s_mov_b32 m0, s45
	ds_read_b128 v[206:209], v218
	ds_read_b128 v[210:213], v218 offset:1024
	ds_read_b128 v[214:217], v218 offset:2048
	ds_read_b128 v[218:221], v218 offset:3072
	global_load_lds_dwordx4 v[222:223], off
	v_lshl_add_u64 v[222:223], v[224:225], 0, s[20:21]
	s_add_i32 m0, s45, 0x2000
	s_nop 0
	global_load_lds_dwordx4 v[222:223], off
	s_barrier
	s_waitcnt lgkmcnt(0)
	s_setprio 1
	s_waitcnt lgkmcnt(0)
	v_mfma_f32_16x16x32_bf16 v[132:135], v[206:209], v[160:163], v[132:135]
	v_mfma_f32_16x16x32_bf16 v[128:131], v[214:217], v[160:163], v[128:131]
	v_mfma_f32_16x16x32_bf16 v[116:119], v[206:209], v[170:173], v[116:119]
	v_mfma_f32_16x16x32_bf16 v[112:115], v[214:217], v[170:173], v[112:115]
	v_mfma_f32_16x16x32_bf16 v[100:103], v[206:209], v[178:181], v[100:103]
	v_mfma_f32_16x16x32_bf16 v[96:99], v[214:217], v[178:181], v[96:99]
	v_mfma_f32_16x16x32_bf16 v[72:75], v[206:209], v[198:201], v[72:75]
	v_mfma_f32_16x16x32_bf16 v[64:67], v[214:217], v[198:201], v[64:67]
	v_mfma_f32_16x16x32_bf16 v[132:135], v[210:213], v[164:167], v[132:135]
	v_mfma_f32_16x16x32_bf16 v[128:131], v[218:221], v[164:167], v[128:131]
	v_mfma_f32_16x16x32_bf16 v[116:119], v[210:213], v[174:177], v[116:119]
	v_mfma_f32_16x16x32_bf16 v[112:115], v[218:221], v[174:177], v[112:115]
	v_mfma_f32_16x16x32_bf16 v[100:103], v[210:213], v[182:185], v[100:103]
	v_mfma_f32_16x16x32_bf16 v[96:99], v[218:221], v[182:185], v[96:99]
	v_mfma_f32_16x16x32_bf16 v[72:75], v[210:213], v[202:205], v[72:75]
	v_mfma_f32_16x16x32_bf16 v[64:67], v[218:221], v[202:205], v[64:67]
	s_setprio 0
	s_mov_b32 m0, s59
	v_lshl_add_u64 v[222:223], v[226:227], 0, s[20:21]
	s_barrier
	ds_read_b128 v[160:163], v195 offset:49152
	ds_read_b128 v[164:167], v195 offset:50176
	ds_read_b128 v[170:173], v195 offset:51200
	ds_read_b128 v[174:177], v195 offset:52224
	ds_read_b128 v[178:181], v195 offset:53248
	ds_read_b128 v[182:185], v195 offset:54272
	ds_read_b128 v[198:201], v195 offset:55296
	ds_read_b128 v[202:205], v195 offset:56320
	global_load_lds_dwordx4 v[222:223], off
	v_lshl_add_u64 v[222:223], v[228:229], 0, s[20:21]
	s_mov_b32 m0, s60
	s_nop 0
	global_load_lds_dwordx4 v[222:223], off
	s_barrier
	s_waitcnt lgkmcnt(0)
	s_setprio 1
	s_waitcnt lgkmcnt(0)
	v_mfma_f32_16x16x32_bf16 v[60:63], v[68:71], v[160:163], v[60:63]
	v_mfma_f32_16x16x32_bf16 v[56:59], v[136:139], v[160:163], v[56:59]
	v_mfma_f32_16x16x32_bf16 v[44:47], v[68:71], v[170:173], v[44:47]
	v_mfma_f32_16x16x32_bf16 v[40:43], v[136:139], v[170:173], v[40:43]
	v_mfma_f32_16x16x32_bf16 v[28:31], v[68:71], v[178:181], v[28:31]
	v_mfma_f32_16x16x32_bf16 v[24:27], v[136:139], v[178:181], v[24:27]
	v_mfma_f32_16x16x32_bf16 v[8:11], v[68:71], v[198:201], v[8:11]
	v_mfma_f32_16x16x32_bf16 v[12:15], v[136:139], v[198:201], v[12:15]
	v_mfma_f32_16x16x32_bf16 v[60:63], v[76:79], v[164:167], v[60:63]
	v_mfma_f32_16x16x32_bf16 v[56:59], v[140:143], v[164:167], v[56:59]
	v_mfma_f32_16x16x32_bf16 v[44:47], v[76:79], v[174:177], v[44:47]
	v_mfma_f32_16x16x32_bf16 v[40:43], v[140:143], v[174:177], v[40:43]
	v_mfma_f32_16x16x32_bf16 v[28:31], v[76:79], v[182:185], v[28:31]
	v_mfma_f32_16x16x32_bf16 v[24:27], v[140:143], v[182:185], v[24:27]
	v_mfma_f32_16x16x32_bf16 v[8:11], v[76:79], v[202:205], v[8:11]
	v_mfma_f32_16x16x32_bf16 v[12:15], v[140:143], v[202:205], v[12:15]
	s_setprio 0
	s_barrier
	s_add_u32 s40, s40, 0x100080
	s_addc_u32 s41, s41, 0
	s_add_i32 s44, s44, s52
	v_lshl_add_u64 v[68:69], s[40:41], 0, v[146:147]
	s_mov_b32 m0, s44
	s_nop 0
	global_load_lds_dwordx4 v[68:69], off
	v_lshl_add_u64 v[68:69], s[40:41], 0, v[150:151]
	s_add_i32 m0, s44, 0x2000
	s_nop 0
	global_load_lds_dwordx4 v[68:69], off
	s_waitcnt vmcnt(6)
	s_barrier
	s_setprio 1
	v_mfma_f32_16x16x32_bf16 v[52:55], v[206:209], v[160:163], v[52:55]
	v_mfma_f32_16x16x32_bf16 v[48:51], v[214:217], v[160:163], v[48:51]
	v_mfma_f32_16x16x32_bf16 v[36:39], v[206:209], v[170:173], v[36:39]
	v_mfma_f32_16x16x32_bf16 v[32:35], v[214:217], v[170:173], v[32:35]
	v_mfma_f32_16x16x32_bf16 v[20:23], v[206:209], v[178:181], v[20:23]
	v_mfma_f32_16x16x32_bf16 v[16:19], v[214:217], v[178:181], v[16:19]
	v_mfma_f32_16x16x32_bf16 v[0:3], v[206:209], v[198:201], v[0:3]
	v_mfma_f32_16x16x32_bf16 v[4:7], v[214:217], v[198:201], v[4:7]
	v_mfma_f32_16x16x32_bf16 v[52:55], v[210:213], v[164:167], v[52:55]
	v_mfma_f32_16x16x32_bf16 v[48:51], v[218:221], v[164:167], v[48:51]
	v_mfma_f32_16x16x32_bf16 v[36:39], v[210:213], v[174:177], v[36:39]
	v_mfma_f32_16x16x32_bf16 v[32:35], v[218:221], v[174:177], v[32:35]
	v_mfma_f32_16x16x32_bf16 v[20:23], v[210:213], v[182:185], v[20:23]
	v_mfma_f32_16x16x32_bf16 v[16:19], v[218:221], v[182:185], v[16:19]
	v_mfma_f32_16x16x32_bf16 v[0:3], v[210:213], v[202:205], v[0:3]
	v_mfma_f32_16x16x32_bf16 v[4:7], v[218:221], v[202:205], v[4:7]
	s_setprio 0
	s_add_i32 s67, s67, 2
	s_add_u32 s0, s0, 0x100
	s_addc_u32 s1, s1, 0
	s_add_u32 s46, s46, 0x100
	s_addc_u32 s47, s47, 0
	s_cmp_gt_u32 s67, 61
	s_barrier
	s_cbranch_scc0 .LBB0_876
	v_add_u32_e32 v224, s39, v192
	ds_read_b128 v[136:139], v224 offset:3072
	ds_read_b128 v[68:71], v224
	ds_read_b128 v[76:79], v224 offset:16
	ds_read_b128 v[140:143], v224 offset:2048
	ds_read_b128 v[164:167], v224 offset:3088
	s_waitcnt lgkmcnt(0)
	v_pk_add_f32 v[160:161], v[138:139], 1.0 op_sel_hi:[1,0]
	v_pk_add_f32 v[162:163], v[136:137], 1.0 op_sel_hi:[1,0]
	ds_read_b128 v[136:139], v224 offset:2064
	v_pk_mul_f32 v[160:161], v[142:143], v[160:161]
	v_pk_mul_f32 v[162:163], v[140:141], v[162:163]
	v_pk_add_f32 v[140:141], v[166:167], 1.0 op_sel_hi:[1,0]
	v_pk_add_f32 v[142:143], v[164:165], 1.0 op_sel_hi:[1,0]
	v_add_u32_e32 v172, s61, v190
	s_waitcnt lgkmcnt(0)
	v_pk_mul_f32 v[164:165], v[138:139], v[140:141]
	v_pk_mul_f32 v[166:167], v[136:137], v[142:143]
	ds_read_b128 v[136:139], v224 offset:3584
	ds_read_b128 v[176:179], v224 offset:2560
	ds_read_b128 v[140:143], v172
	ds_read_b128 v[198:201], v224 offset:3600
	v_add_u32_e32 v182, s33, v188
	ds_read_b128 v[202:205], v172 offset:1024
	v_or_b32_e32 v172, s42, v191
	v_ashrrev_i32_e32 v183, 31, v182
	s_waitcnt lgkmcnt(0)
	v_pk_add_f32 v[170:171], v[138:139], 1.0 op_sel_hi:[1,0]
	v_pk_add_f32 v[210:211], v[136:137], 1.0 op_sel_hi:[1,0]
	v_lshlrev_b32_e32 v136, 16, v140
	v_and_b32_e32 v137, 0xffff0000, v140
	v_lshlrev_b32_e32 v138, 16, v141
	v_and_b32_e32 v139, 0xffff0000, v141
	v_lshlrev_b32_e32 v140, 16, v142
	v_and_b32_e32 v141, 0xffff0000, v142
	v_lshlrev_b32_e32 v142, 16, v143
	v_and_b32_e32 v143, 0xffff0000, v143
	v_ashrrev_i32_e32 v173, 31, v172
	v_lshlrev_b64 v[174:175], 10, v[182:183]
	v_or_b32_e32 v184, 16, v182
	v_lshl_add_u64 v[174:175], v[174:175], 0, v[172:173]
	v_ashrrev_i32_e32 v185, 31, v184
	v_pk_fma_f32 v[94:95], v[94:95], v[70:71], v[138:139]
	v_pk_fma_f32 v[92:93], v[92:93], v[68:69], v[136:137]
	v_pk_fma_f32 v[90:91], v[90:91], v[78:79], v[142:143]
	v_pk_fma_f32 v[88:89], v[88:89], v[76:77], v[140:141]
	v_lshl_add_u64 v[180:181], v[172:173], 1, s[30:31]
	v_lshlrev_b64 v[206:207], 11, v[184:185]
	v_pk_add_f32 v[212:213], v[94:95], 0 op_sel_hi:[1,0]
	v_pk_add_f32 v[214:215], v[92:93], 0 op_sel_hi:[1,0]
	v_pk_add_f32 v[216:217], v[90:91], 0 op_sel_hi:[1,0]
	v_pk_add_f32 v[218:219], v[88:89], 0 op_sel_hi:[1,0]
	v_lshlrev_b64 v[220:221], 1, v[174:175]
	v_lshl_add_u64 v[206:207], v[180:181], 0, v[206:207]
	v_cvt_pk_bf16_f32 v88, v214, v215
	v_cvt_pk_bf16_f32 v89, v212, v213
	v_cvt_pk_bf16_f32 v90, v218, v219
	v_cvt_pk_bf16_f32 v91, v216, v217
	v_lshl_add_u64 v[222:223], s[30:31], 0, v[220:221]
	v_readlane_b32 s40, v243, 54
	global_load_dwordx4 v[140:143], v[206:207], off
	v_pk_mul_f32 v[92:93], v[164:165], v[216:217]
	global_store_dwordx4 v[222:223], v[88:91], off
	v_pk_mul_f32 v[94:95], v[166:167], v[218:219]
	v_readlane_b32 s41, v243, 55
	v_pk_mul_f32 v[90:91], v[160:161], v[212:213]
	v_pk_mul_f32 v[88:89], v[162:163], v[214:215]
	v_pk_mul_f32 v[174:175], v[178:179], v[170:171]
	v_cvt_pk_bf16_f32 v88, v88, v89
	v_cvt_pk_bf16_f32 v89, v90, v91
	v_cvt_pk_bf16_f32 v90, v94, v95
	v_cvt_pk_bf16_f32 v91, v92, v93
	v_lshl_add_u64 v[92:93], s[40:41], 0, v[220:221]
	global_store_dwordx4 v[92:93], v[88:91], off
	global_load_dwordx4 v[136:139], v[206:207], off offset:256
	s_mov_b32 s98, 0x8000
	s_mov_b32 s99, 0
	s_mov_b32 s100, 0x28000
	s_mov_b32 s101, 0
	v_lshl_add_u64 v[248:249], v[206:207], 0, s[98:99]
	global_load_dwordx4 v[244:247], v[248:249], off
	global_load_dwordx4 v[244:247], v[248:249], off offset:256
	v_lshl_add_u64 v[248:249], v[248:249], 0, s[98:99]
	global_load_dwordx4 v[244:247], v[248:249], off
	global_load_dwordx4 v[244:247], v[248:249], off offset:256
	v_lshl_add_u64 v[248:249], v[248:249], 0, s[100:101]
	global_load_dwordx4 v[244:247], v[248:249], off
	global_load_dwordx4 v[244:247], v[248:249], off offset:256
	v_lshl_add_u64 v[248:249], v[248:249], 0, s[98:99]
	global_load_dwordx4 v[244:247], v[248:249], off
	global_load_dwordx4 v[244:247], v[248:249], off offset:256
	v_lshl_add_u64 v[248:249], v[248:249], 0, s[98:99]
	global_load_dwordx4 v[244:247], v[248:249], off
	global_load_dwordx4 v[244:247], v[248:249], off offset:256
	v_lshl_add_u64 v[248:249], v[248:249], 0, s[98:99]
	global_load_dwordx4 v[244:247], v[248:249], off
	global_load_dwordx4 v[244:247], v[248:249], off offset:256
	ds_read_b128 v[206:209], v224 offset:2576
	ds_read_b128 v[88:91], v224 offset:512
	ds_read_b128 v[92:95], v224 offset:528
	v_pk_add_f32 v[170:171], v[200:201], 1.0 op_sel_hi:[1,0]
	v_pk_add_f32 v[198:199], v[198:199], 1.0 op_sel_hi:[1,0]
	v_lshlrev_b32_e32 v200, 16, v202
	s_waitcnt lgkmcnt(0)
	v_pk_mul_f32 v[178:179], v[208:209], v[170:171]
	v_pk_mul_f32 v[170:171], v[206:207], v[198:199]
	v_and_b32_e32 v199, 64, v197
	v_xor_b32_e32 v198, 16, v197
	v_add_u32_e32 v208, 64, v199
	v_cmp_lt_i32_e32 vcc, v198, v208
	v_and_b32_e32 v201, 0xffff0000, v202
	v_lshlrev_b32_e32 v202, 16, v203
	v_and_b32_e32 v203, 0xffff0000, v203
	v_lshlrev_b32_e32 v206, 16, v204
	v_and_b32_e32 v207, 0xffff0000, v204
	v_lshlrev_b32_e32 v204, 16, v205
	v_and_b32_e32 v205, 0xffff0000, v205
	v_cndmask_b32_e32 v198, v197, v198, vcc
	v_lshlrev_b32_e32 v199, 2, v198
	v_xor_b32_e32 v198, 32, v197
	v_pk_fma_f32 v[134:135], v[134:135], v[90:91], v[202:203]
	v_pk_fma_f32 v[132:133], v[132:133], v[88:89], v[200:201]
	v_pk_fma_f32 v[130:131], v[130:131], v[94:95], v[204:205]
	v_pk_fma_f32 v[128:129], v[128:129], v[92:93], v[206:207]
	v_cmp_lt_i32_e32 vcc, v198, v208
	v_mul_f32_e32 v208, v215, v215
	v_mul_f32_e32 v209, v213, v213
	v_pk_add_f32 v[134:135], v[134:135], 0 op_sel_hi:[1,0]
	v_pk_add_f32 v[132:133], v[132:133], 0 op_sel_hi:[1,0]
	v_pk_add_f32 v[200:201], v[130:131], 0 op_sel_hi:[1,0]
	v_pk_add_f32 v[202:203], v[128:129], 0 op_sel_hi:[1,0]
	v_fmac_f32_e32 v208, v214, v214
	v_fmac_f32_e32 v209, v212, v212
	v_cvt_pk_bf16_f32 v128, v132, v133
	v_cvt_pk_bf16_f32 v129, v134, v135
	v_cvt_pk_bf16_f32 v130, v202, v203
	v_cvt_pk_bf16_f32 v131, v200, v201
	v_pk_mul_f32 v[176:177], v[176:177], v[210:211]
	v_add_f32_e32 v208, v208, v209
	v_mul_f32_e32 v209, v219, v219
	v_mul_f32_e32 v210, v217, v217
	global_store_dwordx4 v[222:223], v[128:131], off offset:256
	v_fmac_f32_e32 v209, v218, v218
	v_fmac_f32_e32 v210, v216, v216
	v_mul_f32_e32 v128, v133, v133
	v_mul_f32_e32 v129, v135, v135
	v_fmac_f32_e32 v128, v132, v132
	v_fmac_f32_e32 v129, v134, v134
	v_add_f32_e32 v209, v209, v210
	v_add_f32_e32 v128, v128, v129
	v_mul_f32_e32 v129, v203, v203
	v_mul_f32_e32 v130, v201, v201
	v_add_f32_e32 v208, v208, v209
	v_fmac_f32_e32 v129, v202, v202
	v_fmac_f32_e32 v130, v200, v200
	v_add_f32_e32 v128, v208, v128
	v_add_f32_e32 v129, v129, v130
	v_add_f32_e32 v204, v129, v128
	v_pk_mul_f32 v[128:129], v[174:175], v[134:135]
	v_pk_mul_f32 v[134:135], v[178:179], v[200:201]
	ds_bpermute_b32 v200, v199, v204
	v_cndmask_b32_e32 v198, v197, v198, vcc
	v_pk_mul_f32 v[130:131], v[176:177], v[132:133]
	v_lshlrev_b32_e32 v198, 2, v198
	v_cvt_pk_bf16_f32 v130, v130, v131
	v_cvt_pk_bf16_f32 v131, v128, v129
	s_waitcnt lgkmcnt(0)
	v_add_f32_e32 v128, v204, v200
	ds_bpermute_b32 v129, v198, v128
	s_lshl_b32 s0, s38, 2
	v_pk_mul_f32 v[132:133], v[170:171], v[202:203]
	v_or_b32_e32 v220, 0x100, v220
	s_ashr_i32 s1, s0, 31
	v_cvt_pk_bf16_f32 v132, v132, v133
	v_cvt_pk_bf16_f32 v133, v134, v135
	v_lshl_add_u64 v[134:135], s[40:41], 0, v[220:221]
	global_store_dwordx4 v[134:135], v[130:133], off
	s_and_saveexec_b64 s[38:39], s[4:5]
	s_cbranch_execz .LBB0_879
	v_lshlrev_b64 v[130:131], 6, v[182:183]
	v_lshl_add_u64 v[130:131], s[16:17], 0, v[130:131]
	v_lshl_add_u64 v[130:131], s[0:1], 2, v[130:131]
	s_lshl_b32 s40, s58, 2
	s_mov_b32 s41, s3
	v_lshl_add_u64 v[130:131], v[130:131], 0, s[40:41]
	s_waitcnt lgkmcnt(0)
	v_add_f32_e32 v128, v128, v129
	global_store_dword v[130:131], v128, off

.Lat_m1_nodiag:
	v_add_f32_e32 v189, v80, v81
	v_add_f32_e32 v190, v82, v83
	v_add_f32_e32 v191, v84, v85
	v_add_f32_e32 v192, v86, v87
	v_add_f32_e32 v193, v88, v89
	v_add_f32_e32 v194, v90, v91
	v_add_f32_e32 v195, v92, v93
	v_add_f32_e32 v196, v94, v95
	v_cvt_pk_bf16_f32 v80, v80, v81
	v_cvt_pk_bf16_f32 v81, v82, v83
	v_cvt_pk_bf16_f32 v82, v84, v85
	v_cvt_pk_bf16_f32 v83, v86, v87
	v_cvt_pk_bf16_f32 v84, v88, v89
	v_cvt_pk_bf16_f32 v85, v90, v91
	v_cvt_pk_bf16_f32 v86, v92, v93
	v_cvt_pk_bf16_f32 v87, v94, v95
	v_add_f32_e32 v189, v189, v190
	v_add_f32_e32 v191, v191, v192
	v_add_f32_e32 v193, v193, v194
	v_add_f32_e32 v195, v195, v196
	v_add_f32_e32 v189, v189, v191
	v_add_f32_e32 v193, v193, v195
	v_add_f32_e32 v189, v189, v193
	v_add_f32_e32 v187, v187, v189
	s_waitcnt lgkmcnt(4)
	v_mfma_f32_32x32x16_bf16 v[32:47], v[220:223], v[80:83], v[32:47]
	v_mfma_f32_32x32x16_bf16 v[16:31], v[224:227], v[80:83], v[16:31]
	v_mfma_f32_32x32x16_bf16 v[32:47], v[228:231], v[84:87], v[32:47]
	v_mfma_f32_32x32x16_bf16 v[16:31], v[232:235], v[84:87], v[16:31]
	s_add_i32 s70, s70, 1
	s_cmp_le_u32 s70, s71
	s_cbranch_scc1 .Lat_m1_tile

	s_xor_b32 s33, s33, 1
	s_and_b64 vcc, exec, s[12:13]
	s_cbranch_vccz .LBB0_1200
	s_mul_i32 s0, s33, 0x8a00
	s_add_i32 s0, s0, 0
	v_add3_u32 v80, s0, v178, v144
	s_waitcnt vmcnt(2)
	ds_write_b128 v80, v[116:119]
	ds_write_b128 v80, v[112:115] offset:16
	v_lshl_add_u32 v80, v152, 1, s0
	s_waitcnt vmcnt(1)
	ds_write_b16 v80, v120 offset:18432
	ds_write_b16_d16_hi v80, v120 offset:18696
	ds_write_b16 v80, v121 offset:18960
	ds_write_b16_d16_hi v80, v121 offset:19224
	ds_write_b16 v80, v122 offset:19488
	ds_write_b16_d16_hi v80, v122 offset:19752
	ds_write_b16 v80, v123 offset:20016
	ds_write_b16_d16_hi v80, v123 offset:20280
	s_waitcnt vmcnt(0)
	ds_write_b16 v80, v124 offset:20544
	ds_write_b16_d16_hi v80, v124 offset:20808
	ds_write_b16 v80, v125 offset:21072
	ds_write_b16_d16_hi v80, v125 offset:21336
	ds_write_b16 v80, v126 offset:21600
	ds_write_b16_d16_hi v80, v126 offset:21864
	ds_write_b16 v80, v127 offset:22128
	ds_write_b16_d16_hi v80, v127 offset:22392

.LBB0_1299:
	s_waitcnt lgkmcnt(0)
	v_pk_add_f32 v[166:167], v[166:167], 1.0 op_sel_hi:[1,0]
	v_pk_add_f32 v[164:165], v[164:165], 1.0 op_sel_hi:[1,0]
	v_add_u32_e32 v214, s72, v207
	v_pk_mul_f32 v[162:163], v[162:163], v[166:167]
	v_pk_mul_f32 v[160:161], v[160:161], v[164:165]
	v_pk_add_f32 v[164:165], v[158:159], 1.0 op_sel_hi:[1,0]
	v_pk_add_f32 v[166:167], v[156:157], 1.0 op_sel_hi:[1,0]
	ds_read_b128 v[156:159], v214
	v_pk_mul_f32 v[154:155], v[154:155], v[164:165]
	v_add_u32_e32 v164, s33, v205
	v_ashrrev_i32_e32 v165, 31, v164
	v_pk_mul_f32 v[152:153], v[152:153], v[166:167]
	s_waitcnt lgkmcnt(0)
	v_lshlrev_b32_e32 v218, 16, v156
	v_and_b32_e32 v219, 0xffff0000, v156
	v_or_b32_e32 v156, s46, v208
	v_lshlrev_b32_e32 v220, 16, v157
	v_and_b32_e32 v221, 0xffff0000, v157
	s_and_b64 s[0:1], s[44:45], exec
	v_ashrrev_i32_e32 v157, 31, v156
	v_lshlrev_b64 v[166:167], 10, v[164:165]
	v_lshlrev_b32_e32 v222, 16, v158
	v_and_b32_e32 v223, 0xffff0000, v158
	v_lshlrev_b32_e32 v224, 16, v159
	v_and_b32_e32 v225, 0xffff0000, v159
	v_readlane_b32 s0, v242, 24
	v_lshl_add_u64 v[226:227], v[166:167], 0, v[156:157]
	v_or_b32_e32 v166, 16, v164
	s_cselect_b32 s1, s9, s0
	v_readlane_b32 s0, v242, 23
	v_ashrrev_i32_e32 v167, 31, v166
	v_pk_fma_f32 v[140:141], v[140:141], v[64:65], v[218:219]
	v_pk_fma_f32 v[142:143], v[142:143], v[66:67], v[220:221]
	v_pk_fma_f32 v[136:137], v[136:137], v[80:81], v[222:223]
	v_pk_fma_f32 v[138:139], v[138:139], v[82:83], v[224:225]
	s_cselect_b32 s0, s8, s0
	v_lshl_add_u64 v[158:159], v[156:157], 1, s[42:43]
	v_lshlrev_b64 v[228:229], 11, v[166:167]
	v_pk_add_f32 v[230:231], v[188:189], v[142:143]
	v_pk_add_f32 v[232:233], v[186:187], v[140:141]
	v_pk_add_f32 v[234:235], v[198:199], v[138:139]
	v_pk_add_f32 v[236:237], v[190:191], v[136:137]
	v_lshlrev_b64 v[226:227], 1, v[226:227]
	v_lshl_add_u64 v[228:229], v[158:159], 0, v[228:229]
	v_cvt_pk_bf16_f32 v136, v232, v233
	v_cvt_pk_bf16_f32 v137, v230, v231
	v_cvt_pk_bf16_f32 v138, v236, v237
	v_cvt_pk_bf16_f32 v139, v234, v235
	v_lshl_add_u64 v[238:239], s[0:1], 0, v[226:227]
	global_load_dwordx4 v[140:143], v[228:229], off
	v_pk_mul_f32 v[218:219], v[162:163], v[234:235]
	global_store_dwordx4 v[238:239], v[136:139], off
	v_pk_mul_f32 v[220:221], v[160:161], v[236:237]
	ds_read_b128 v[214:217], v214 offset:1024
	v_pk_mul_f32 v[138:139], v[154:155], v[230:231]
	v_pk_mul_f32 v[136:137], v[152:153], v[232:233]
	v_pk_add_f32 v[150:151], v[150:151], 1.0 op_sel_hi:[1,0]
	v_cvt_pk_bf16_f32 v136, v136, v137
	v_cvt_pk_bf16_f32 v137, v138, v139
	v_cvt_pk_bf16_f32 v138, v220, v221
	v_cvt_pk_bf16_f32 v139, v218, v219
	v_lshl_add_u64 v[218:219], s[6:7], 0, v[226:227]
	global_store_dwordx4 v[218:219], v[136:139], off
	global_load_dwordx4 v[136:139], v[228:229], off offset:256
	s_mov_b32 s98, 0x8000
	s_mov_b32 s99, 0
	s_mov_b32 s100, 0x28000
	s_mov_b32 s101, 0
	v_lshl_add_u64 v[248:249], v[228:229], 0, s[98:99]
	global_load_dwordx4 v[244:247], v[248:249], off
	global_load_dwordx4 v[244:247], v[248:249], off offset:256
	v_lshl_add_u64 v[248:249], v[248:249], 0, s[98:99]
	global_load_dwordx4 v[244:247], v[248:249], off
	global_load_dwordx4 v[244:247], v[248:249], off offset:256
	v_lshl_add_u64 v[248:249], v[248:249], 0, s[100:101]
	global_load_dwordx4 v[244:247], v[248:249], off
	global_load_dwordx4 v[244:247], v[248:249], off offset:256
	v_lshl_add_u64 v[248:249], v[248:249], 0, s[98:99]
	global_load_dwordx4 v[244:247], v[248:249], off
	global_load_dwordx4 v[244:247], v[248:249], off offset:256
	v_lshl_add_u64 v[248:249], v[248:249], 0, s[98:99]
	global_load_dwordx4 v[244:247], v[248:249], off
	global_load_dwordx4 v[244:247], v[248:249], off offset:256
	v_lshl_add_u64 v[248:249], v[248:249], 0, s[98:99]
	global_load_dwordx4 v[244:247], v[248:249], off
	global_load_dwordx4 v[244:247], v[248:249], off offset:256
	ds_read_b128 v[218:221], v213 offset:2576
	ds_read_b128 v[222:225], v213 offset:3600
	v_pk_add_f32 v[228:229], v[148:149], 1.0 op_sel_hi:[1,0]
	v_pk_mul_f32 v[148:149], v[146:147], v[150:151]
	v_pk_mul_f32 v[150:151], v[144:145], v[228:229]
	v_mul_f32_e32 v213, v233, v233
	s_waitcnt lgkmcnt(0)
	v_pk_add_f32 v[144:145], v[224:225], 1.0 op_sel_hi:[1,0]
	v_pk_add_f32 v[222:223], v[222:223], 1.0 op_sel_hi:[1,0]
	v_pk_mul_f32 v[146:147], v[220:221], v[144:145]
	v_pk_mul_f32 v[144:145], v[218:219], v[222:223]
	v_lshlrev_b32_e32 v218, 16, v214
	v_and_b32_e32 v219, 0xffff0000, v214
	v_lshlrev_b32_e32 v214, 16, v215
	v_and_b32_e32 v215, 0xffff0000, v215
	v_lshlrev_b32_e32 v220, 16, v216
	v_and_b32_e32 v221, 0xffff0000, v216
	v_lshlrev_b32_e32 v216, 16, v217
	v_and_b32_e32 v217, 0xffff0000, v217
	v_pk_fma_f32 v[132:133], v[132:133], v[76:77], v[218:219]
	v_pk_fma_f32 v[134:135], v[134:135], v[78:79], v[214:215]
	v_pk_fma_f32 v[128:129], v[128:129], v[84:85], v[220:221]
	v_pk_fma_f32 v[130:131], v[130:131], v[86:87], v[216:217]
	v_mul_f32_e32 v222, v231, v231
	v_pk_add_f32 v[134:135], v[192:193], v[134:135]
	v_pk_add_f32 v[132:133], v[194:195], v[132:133]
	v_pk_add_f32 v[214:215], v[200:201], v[130:131]
	v_pk_add_f32 v[216:217], v[196:197], v[128:129]
	v_fmac_f32_e32 v213, v232, v232
	v_fmac_f32_e32 v222, v230, v230
	v_cvt_pk_bf16_f32 v128, v132, v133
	v_cvt_pk_bf16_f32 v129, v134, v135
	v_cvt_pk_bf16_f32 v130, v216, v217
	v_cvt_pk_bf16_f32 v131, v214, v215
	v_add_f32_e32 v213, v213, v222
	v_mul_f32_e32 v222, v237, v237
	v_mul_f32_e32 v223, v235, v235
	global_store_dwordx4 v[238:239], v[128:131], off offset:256
	v_fmac_f32_e32 v222, v236, v236
	v_fmac_f32_e32 v223, v234, v234
	v_mul_f32_e32 v128, v133, v133
	v_mul_f32_e32 v129, v135, v135
	v_fmac_f32_e32 v128, v132, v132
	v_fmac_f32_e32 v129, v134, v134
	v_add_f32_e32 v222, v222, v223
	v_add_f32_e32 v128, v128, v129
	v_mul_f32_e32 v129, v217, v217
	v_mul_f32_e32 v130, v215, v215
	v_add_f32_e32 v213, v213, v222
	v_fmac_f32_e32 v129, v216, v216
	v_fmac_f32_e32 v130, v214, v214
	v_add_f32_e32 v128, v213, v128
	v_add_f32_e32 v129, v129, v130
	v_add_f32_e32 v213, v129, v128
	v_pk_mul_f32 v[128:129], v[148:149], v[134:135]
	v_pk_mul_f32 v[134:135], v[146:147], v[214:215]
	ds_bpermute_b32 v214, v169, v213
	v_pk_mul_f32 v[130:131], v[150:151], v[132:133]
	s_lshl_b32 s40, s40, 2
	v_cvt_pk_bf16_f32 v130, v130, v131
	v_cvt_pk_bf16_f32 v131, v128, v129
	s_waitcnt lgkmcnt(0)
	v_add_f32_e32 v128, v213, v214
	ds_bpermute_b32 v129, v202, v128
	v_pk_mul_f32 v[132:133], v[144:145], v[216:217]
	v_or_b32_e32 v226, 0x100, v226
	s_ashr_i32 s41, s40, 31
	v_cvt_pk_bf16_f32 v132, v132, v133
	v_cvt_pk_bf16_f32 v133, v134, v135
	v_lshl_add_u64 v[134:135], s[6:7], 0, v[226:227]
	global_store_dwordx4 v[134:135], v[130:133], off
	s_and_saveexec_b64 s[42:43], s[2:3]
	s_cbranch_execz .LBB0_1301
	v_lshlrev_b64 v[130:131], 6, v[164:165]
	v_lshl_add_u64 v[130:131], s[10:11], 0, v[130:131]
	v_lshl_add_u64 v[130:131], s[40:41], 2, v[130:131]
	s_lshl_b32 s44, s69, 2
	s_mov_b32 s45, s13
	v_lshl_add_u64 v[130:131], v[130:131], 0, s[44:45]
	s_waitcnt lgkmcnt(0)
	v_add_f32_e32 v128, v128, v129
	global_store_dword v[130:131], v128, off

.LBB0_1515:
	ds_read_b128 v[104:107], v165
	ds_read_b128 v[108:111], v165 offset:1024
	ds_read_b128 v[152:155], v165 offset:2048
	ds_read_b128 v[168:171], v165 offset:3072
	s_add_u32 s30, s2, 0xfff00080
	s_addc_u32 s31, s3, -1
	s_cmp_eq_u32 s60, 60
	s_cselect_b32 s35, s19, s31
	s_cselect_b32 s34, s29, s30
	s_cselect_b32 s31, s17, s59
	s_cselect_b32 s30, s36, s58
	v_lshl_add_u64 v[156:157], s[2:3], 0, v[144:145]
	s_add_i32 m0, s37, 0xc000
	ds_read_b128 v[172:175], v166
	ds_read_b128 v[176:179], v166 offset:1024
	ds_read_b128 v[180:183], v166 offset:2048
	ds_read_b128 v[184:187], v166 offset:3072
	ds_read_b128 v[188:191], v166 offset:4096
	ds_read_b128 v[192:195], v166 offset:5120
	ds_read_b128 v[196:199], v166 offset:6144
	ds_read_b128 v[200:203], v166 offset:7168
	global_load_lds_dwordx4 v[156:157], off
	v_lshl_add_u64 v[156:157], s[2:3], 0, v[146:147]
	s_add_i32 m0, s37, 0xe000
	s_nop 0
	global_load_lds_dwordx4 v[156:157], off
	s_waitcnt lgkmcnt(8)
	s_barrier
	s_waitcnt lgkmcnt(0)
	s_setprio 1
	s_waitcnt lgkmcnt(0)
	v_mfma_f32_16x16x32_bf16 v[132:135], v[104:107], v[172:175], v[132:135]
	v_mfma_f32_16x16x32_bf16 v[128:131], v[152:155], v[172:175], v[128:131]
	v_mfma_f32_16x16x32_bf16 v[116:119], v[104:107], v[180:183], v[116:119]
	v_mfma_f32_16x16x32_bf16 v[112:115], v[152:155], v[180:183], v[112:115]
	v_mfma_f32_16x16x32_bf16 v[92:95], v[104:107], v[188:191], v[92:95]
	v_mfma_f32_16x16x32_bf16 v[88:91], v[152:155], v[188:191], v[88:91]
	v_mfma_f32_16x16x32_bf16 v[76:79], v[104:107], v[196:199], v[76:79]
	v_mfma_f32_16x16x32_bf16 v[72:75], v[152:155], v[196:199], v[72:75]
	v_mfma_f32_16x16x32_bf16 v[132:135], v[108:111], v[176:179], v[132:135]
	v_mfma_f32_16x16x32_bf16 v[128:131], v[168:171], v[176:179], v[128:131]
	v_mfma_f32_16x16x32_bf16 v[116:119], v[108:111], v[184:187], v[116:119]
	v_mfma_f32_16x16x32_bf16 v[112:115], v[168:171], v[184:187], v[112:115]
	v_mfma_f32_16x16x32_bf16 v[92:95], v[108:111], v[192:195], v[92:95]
	v_mfma_f32_16x16x32_bf16 v[88:91], v[168:171], v[192:195], v[88:91]
	v_mfma_f32_16x16x32_bf16 v[76:79], v[108:111], v[200:203], v[76:79]
	v_mfma_f32_16x16x32_bf16 v[72:75], v[168:171], v[200:203], v[72:75]
	s_setprio 0
	s_barrier
	s_add_i32 s61, s53, s40
	v_lshl_add_u64 v[156:157], s[30:31], 0, v[140:141]
	s_mov_b32 m0, s61
	ds_read_b128 v[204:207], v167
	ds_read_b128 v[208:211], v167 offset:1024
	ds_read_b128 v[212:215], v167 offset:2048
	ds_read_b128 v[216:219], v167 offset:3072
	global_load_lds_dwordx4 v[156:157], off
	v_lshl_add_u64 v[220:221], s[30:31], 0, v[136:137]
	s_add_i32 m0, s61, 0x2000
	s_nop 0
	global_load_lds_dwordx4 v[220:221], off
	s_barrier
	s_waitcnt lgkmcnt(0)
	s_setprio 1
	s_waitcnt lgkmcnt(0)
	v_mfma_f32_16x16x32_bf16 v[124:127], v[204:207], v[172:175], v[124:127]
	v_mfma_f32_16x16x32_bf16 v[120:123], v[212:215], v[172:175], v[120:123]
	v_mfma_f32_16x16x32_bf16 v[100:103], v[204:207], v[180:183], v[100:103]
	v_mfma_f32_16x16x32_bf16 v[96:99], v[212:215], v[180:183], v[96:99]
	v_mfma_f32_16x16x32_bf16 v[84:87], v[204:207], v[188:191], v[84:87]
	v_mfma_f32_16x16x32_bf16 v[80:83], v[212:215], v[188:191], v[80:83]
	v_mfma_f32_16x16x32_bf16 v[68:71], v[204:207], v[196:199], v[68:71]
	v_mfma_f32_16x16x32_bf16 v[64:67], v[212:215], v[196:199], v[64:67]
	v_mfma_f32_16x16x32_bf16 v[124:127], v[208:211], v[176:179], v[124:127]
	v_mfma_f32_16x16x32_bf16 v[120:123], v[216:219], v[176:179], v[120:123]
	v_mfma_f32_16x16x32_bf16 v[100:103], v[208:211], v[184:187], v[100:103]
	v_mfma_f32_16x16x32_bf16 v[96:99], v[216:219], v[184:187], v[96:99]
	v_mfma_f32_16x16x32_bf16 v[84:87], v[208:211], v[192:195], v[84:87]
	v_mfma_f32_16x16x32_bf16 v[80:83], v[216:219], v[192:195], v[80:83]
	v_mfma_f32_16x16x32_bf16 v[68:71], v[208:211], v[200:203], v[68:71]
	v_mfma_f32_16x16x32_bf16 v[64:67], v[216:219], v[200:203], v[64:67]
	s_setprio 0
	s_mov_b32 m0, s37
	v_lshl_add_u64 v[222:223], s[34:35], 0, v[142:143]
	s_barrier
	ds_read_b128 v[172:175], v166 offset:16384
	ds_read_b128 v[176:179], v166 offset:17408
	ds_read_b128 v[180:183], v166 offset:18432
	ds_read_b128 v[184:187], v166 offset:19456
	ds_read_b128 v[188:191], v166 offset:20480
	ds_read_b128 v[192:195], v166 offset:21504
	ds_read_b128 v[196:199], v166 offset:22528
	ds_read_b128 v[200:203], v166 offset:23552
	global_load_lds_dwordx4 v[222:223], off
	v_lshl_add_u64 v[224:225], s[34:35], 0, v[138:139]
	s_mov_b32 m0, s41
	s_nop 0
	global_load_lds_dwordx4 v[224:225], off
	s_barrier
	s_waitcnt lgkmcnt(0)
	s_setprio 1
	s_waitcnt lgkmcnt(0)
	v_mfma_f32_16x16x32_bf16 v[60:63], v[104:107], v[172:175], v[60:63]
	v_mfma_f32_16x16x32_bf16 v[56:59], v[152:155], v[172:175], v[56:59]
	v_mfma_f32_16x16x32_bf16 v[44:47], v[104:107], v[180:183], v[44:47]
	v_mfma_f32_16x16x32_bf16 v[40:43], v[152:155], v[180:183], v[40:43]
	v_mfma_f32_16x16x32_bf16 v[28:31], v[104:107], v[188:191], v[28:31]
	v_mfma_f32_16x16x32_bf16 v[24:27], v[152:155], v[188:191], v[24:27]
	v_mfma_f32_16x16x32_bf16 v[20:23], v[104:107], v[196:199], v[20:23]
	v_mfma_f32_16x16x32_bf16 v[16:19], v[152:155], v[196:199], v[16:19]
	v_mfma_f32_16x16x32_bf16 v[60:63], v[108:111], v[176:179], v[60:63]
	v_mfma_f32_16x16x32_bf16 v[56:59], v[168:171], v[176:179], v[56:59]
	v_mfma_f32_16x16x32_bf16 v[44:47], v[108:111], v[184:187], v[44:47]
	v_mfma_f32_16x16x32_bf16 v[40:43], v[168:171], v[184:187], v[40:43]
	v_mfma_f32_16x16x32_bf16 v[28:31], v[108:111], v[192:195], v[28:31]
	v_mfma_f32_16x16x32_bf16 v[24:27], v[168:171], v[192:195], v[24:27]
	v_mfma_f32_16x16x32_bf16 v[20:23], v[108:111], v[200:203], v[20:23]
	v_mfma_f32_16x16x32_bf16 v[16:19], v[168:171], v[200:203], v[16:19]
	s_setprio 0
	s_barrier
	s_add_u32 s62, s30, 0x100000
	s_addc_u32 s63, s31, 0
	s_add_i32 s61, s54, s40
	v_lshl_add_u64 v[104:105], s[62:63], 0, v[140:141]
	s_mov_b32 m0, s61
	s_nop 0
	global_load_lds_dwordx4 v[104:105], off
	v_lshl_add_u64 v[104:105], s[62:63], 0, v[136:137]
	s_add_i32 m0, s61, 0x2000
	s_nop 0
	global_load_lds_dwordx4 v[104:105], off
	s_waitcnt vmcnt(6)
	s_barrier
	s_setprio 1
	v_mfma_f32_16x16x32_bf16 v[52:55], v[204:207], v[172:175], v[52:55]
	v_mfma_f32_16x16x32_bf16 v[48:51], v[212:215], v[172:175], v[48:51]
	v_mfma_f32_16x16x32_bf16 v[36:39], v[204:207], v[180:183], v[36:39]
	v_mfma_f32_16x16x32_bf16 v[32:35], v[212:215], v[180:183], v[32:35]
	v_mfma_f32_16x16x32_bf16 v[12:15], v[204:207], v[188:191], v[12:15]
	v_mfma_f32_16x16x32_bf16 v[8:11], v[212:215], v[188:191], v[8:11]
	v_mfma_f32_16x16x32_bf16 v[4:7], v[204:207], v[196:199], v[4:7]
	v_mfma_f32_16x16x32_bf16 v[0:3], v[212:215], v[196:199], v[0:3]
	v_mfma_f32_16x16x32_bf16 v[52:55], v[208:211], v[176:179], v[52:55]
	v_mfma_f32_16x16x32_bf16 v[48:51], v[216:219], v[176:179], v[48:51]
	v_mfma_f32_16x16x32_bf16 v[36:39], v[208:211], v[184:187], v[36:39]
	v_mfma_f32_16x16x32_bf16 v[32:35], v[216:219], v[184:187], v[32:35]
	v_mfma_f32_16x16x32_bf16 v[12:15], v[208:211], v[192:195], v[12:15]
	v_mfma_f32_16x16x32_bf16 v[8:11], v[216:219], v[192:195], v[8:11]
	v_mfma_f32_16x16x32_bf16 v[4:7], v[208:211], v[200:203], v[4:7]
	v_mfma_f32_16x16x32_bf16 v[0:3], v[216:219], v[200:203], v[0:3]
	s_setprio 0
	s_add_i32 s61, 0, 0x18000
	v_add_u32_e32 v168, s61, v161
	s_barrier
	ds_read_b128 v[104:107], v168
	ds_read_b128 v[108:111], v168 offset:1024
	ds_read_b128 v[152:155], v168 offset:2048
	ds_read_b128 v[168:171], v168 offset:3072
	s_add_u32 s34, s34, 0x100000
	s_addc_u32 s35, s35, 0
	s_mov_b32 m0, s42
	v_lshl_add_u64 v[204:205], s[34:35], 0, v[142:143]
	ds_read_b128 v[172:175], v166 offset:32768
	ds_read_b128 v[176:179], v166 offset:33792
	ds_read_b128 v[180:183], v166 offset:34816
	ds_read_b128 v[184:187], v166 offset:35840
	ds_read_b128 v[188:191], v166 offset:36864
	ds_read_b128 v[192:195], v166 offset:37888
	ds_read_b128 v[196:199], v166 offset:38912
	ds_read_b128 v[200:203], v166 offset:39936
	global_load_lds_dwordx4 v[204:205], off
	v_lshl_add_u64 v[204:205], s[34:35], 0, v[138:139]
	s_mov_b32 m0, s43
	s_nop 0
	global_load_lds_dwordx4 v[204:205], off
	s_waitcnt lgkmcnt(8)
	s_barrier
	s_waitcnt lgkmcnt(0)
	s_setprio 1
	s_waitcnt lgkmcnt(0)
	v_mfma_f32_16x16x32_bf16 v[132:135], v[104:107], v[172:175], v[132:135]
	v_mfma_f32_16x16x32_bf16 v[128:131], v[152:155], v[172:175], v[128:131]
	v_mfma_f32_16x16x32_bf16 v[116:119], v[104:107], v[180:183], v[116:119]
	v_mfma_f32_16x16x32_bf16 v[112:115], v[152:155], v[180:183], v[112:115]
	v_mfma_f32_16x16x32_bf16 v[92:95], v[104:107], v[188:191], v[92:95]
	v_mfma_f32_16x16x32_bf16 v[88:91], v[152:155], v[188:191], v[88:91]
	v_mfma_f32_16x16x32_bf16 v[76:79], v[104:107], v[196:199], v[76:79]
	v_mfma_f32_16x16x32_bf16 v[72:75], v[152:155], v[196:199], v[72:75]
	v_mfma_f32_16x16x32_bf16 v[132:135], v[108:111], v[176:179], v[132:135]
	v_mfma_f32_16x16x32_bf16 v[128:131], v[168:171], v[176:179], v[128:131]
	v_mfma_f32_16x16x32_bf16 v[116:119], v[108:111], v[184:187], v[116:119]
	v_mfma_f32_16x16x32_bf16 v[112:115], v[168:171], v[184:187], v[112:115]
	v_mfma_f32_16x16x32_bf16 v[92:95], v[108:111], v[192:195], v[92:95]
	v_mfma_f32_16x16x32_bf16 v[88:91], v[168:171], v[192:195], v[88:91]
	v_mfma_f32_16x16x32_bf16 v[76:79], v[108:111], v[200:203], v[76:79]
	v_mfma_f32_16x16x32_bf16 v[72:75], v[168:171], v[200:203], v[72:75]
	s_setprio 0
	s_barrier
	s_add_i32 s34, 0, 0x1c000
	s_add_i32 s35, s61, s40
	v_add_u32_e32 v216, s34, v161
	v_lshl_add_u64 v[156:157], v[156:157], 0, s[6:7]
	s_mov_b32 m0, s35
	ds_read_b128 v[204:207], v216
	ds_read_b128 v[208:211], v216 offset:1024
	ds_read_b128 v[212:215], v216 offset:2048
	ds_read_b128 v[216:219], v216 offset:3072
	global_load_lds_dwordx4 v[156:157], off
	v_lshl_add_u64 v[156:157], v[220:221], 0, s[6:7]
	s_add_i32 m0, s35, 0x2000
	s_nop 0
	global_load_lds_dwordx4 v[156:157], off
	s_barrier
	s_waitcnt lgkmcnt(0)
	s_setprio 1
	s_waitcnt lgkmcnt(0)
	v_mfma_f32_16x16x32_bf16 v[124:127], v[204:207], v[172:175], v[124:127]
	v_mfma_f32_16x16x32_bf16 v[120:123], v[212:215], v[172:175], v[120:123]
	v_mfma_f32_16x16x32_bf16 v[100:103], v[204:207], v[180:183], v[100:103]
	v_mfma_f32_16x16x32_bf16 v[96:99], v[212:215], v[180:183], v[96:99]
	v_mfma_f32_16x16x32_bf16 v[84:87], v[204:207], v[188:191], v[84:87]
	v_mfma_f32_16x16x32_bf16 v[80:83], v[212:215], v[188:191], v[80:83]
	v_mfma_f32_16x16x32_bf16 v[68:71], v[204:207], v[196:199], v[68:71]
	v_mfma_f32_16x16x32_bf16 v[64:67], v[212:215], v[196:199], v[64:67]
	v_mfma_f32_16x16x32_bf16 v[124:127], v[208:211], v[176:179], v[124:127]
	v_mfma_f32_16x16x32_bf16 v[120:123], v[216:219], v[176:179], v[120:123]
	v_mfma_f32_16x16x32_bf16 v[100:103], v[208:211], v[184:187], v[100:103]
	v_mfma_f32_16x16x32_bf16 v[96:99], v[216:219], v[184:187], v[96:99]
	v_mfma_f32_16x16x32_bf16 v[84:87], v[208:211], v[192:195], v[84:87]
	v_mfma_f32_16x16x32_bf16 v[80:83], v[216:219], v[192:195], v[80:83]
	v_mfma_f32_16x16x32_bf16 v[68:71], v[208:211], v[200:203], v[68:71]
	v_mfma_f32_16x16x32_bf16 v[64:67], v[216:219], v[200:203], v[64:67]
	s_setprio 0
	s_mov_b32 m0, s48
	v_lshl_add_u64 v[156:157], v[222:223], 0, s[6:7]
	s_barrier
	ds_read_b128 v[172:175], v166 offset:49152
	ds_read_b128 v[176:179], v166 offset:50176
	ds_read_b128 v[180:183], v166 offset:51200
	ds_read_b128 v[184:187], v166 offset:52224
	ds_read_b128 v[188:191], v166 offset:53248
	ds_read_b128 v[192:195], v166 offset:54272
	ds_read_b128 v[196:199], v166 offset:55296
	ds_read_b128 v[200:203], v166 offset:56320
	global_load_lds_dwordx4 v[156:157], off
	v_lshl_add_u64 v[156:157], v[224:225], 0, s[6:7]
	s_mov_b32 m0, s49
	s_nop 0
	global_load_lds_dwordx4 v[156:157], off
	s_barrier
	s_waitcnt lgkmcnt(0)
	s_setprio 1
	s_waitcnt lgkmcnt(0)
	v_mfma_f32_16x16x32_bf16 v[60:63], v[104:107], v[172:175], v[60:63]
	v_mfma_f32_16x16x32_bf16 v[56:59], v[152:155], v[172:175], v[56:59]
	v_mfma_f32_16x16x32_bf16 v[44:47], v[104:107], v[180:183], v[44:47]
	v_mfma_f32_16x16x32_bf16 v[40:43], v[152:155], v[180:183], v[40:43]
	v_mfma_f32_16x16x32_bf16 v[28:31], v[104:107], v[188:191], v[28:31]
	v_mfma_f32_16x16x32_bf16 v[24:27], v[152:155], v[188:191], v[24:27]
	v_mfma_f32_16x16x32_bf16 v[20:23], v[104:107], v[196:199], v[20:23]
	v_mfma_f32_16x16x32_bf16 v[16:19], v[152:155], v[196:199], v[16:19]
	v_mfma_f32_16x16x32_bf16 v[60:63], v[108:111], v[176:179], v[60:63]
	v_mfma_f32_16x16x32_bf16 v[56:59], v[168:171], v[176:179], v[56:59]
	v_mfma_f32_16x16x32_bf16 v[44:47], v[108:111], v[184:187], v[44:47]
	v_mfma_f32_16x16x32_bf16 v[40:43], v[168:171], v[184:187], v[40:43]
	v_mfma_f32_16x16x32_bf16 v[28:31], v[108:111], v[192:195], v[28:31]
	v_mfma_f32_16x16x32_bf16 v[24:27], v[168:171], v[192:195], v[24:27]
	v_mfma_f32_16x16x32_bf16 v[20:23], v[108:111], v[200:203], v[20:23]
	v_mfma_f32_16x16x32_bf16 v[16:19], v[168:171], v[200:203], v[16:19]
	s_setprio 0
	s_barrier
	s_add_u32 s30, s30, 0x100080
	s_addc_u32 s31, s31, 0
	s_add_i32 s34, s34, s40
	v_lshl_add_u64 v[104:105], s[30:31], 0, v[140:141]
	s_mov_b32 m0, s34
	s_nop 0
	global_load_lds_dwordx4 v[104:105], off
	v_lshl_add_u64 v[104:105], s[30:31], 0, v[136:137]
	s_add_i32 m0, s34, 0x2000
	s_nop 0
	global_load_lds_dwordx4 v[104:105], off
	s_waitcnt vmcnt(6)
	s_barrier
	s_setprio 1
	v_mfma_f32_16x16x32_bf16 v[52:55], v[204:207], v[172:175], v[52:55]
	v_mfma_f32_16x16x32_bf16 v[48:51], v[212:215], v[172:175], v[48:51]
	v_mfma_f32_16x16x32_bf16 v[36:39], v[204:207], v[180:183], v[36:39]
	v_mfma_f32_16x16x32_bf16 v[32:35], v[212:215], v[180:183], v[32:35]
	v_mfma_f32_16x16x32_bf16 v[12:15], v[204:207], v[188:191], v[12:15]
	v_mfma_f32_16x16x32_bf16 v[8:11], v[212:215], v[188:191], v[8:11]
	v_mfma_f32_16x16x32_bf16 v[4:7], v[204:207], v[196:199], v[4:7]
	v_mfma_f32_16x16x32_bf16 v[0:3], v[212:215], v[196:199], v[0:3]
	v_mfma_f32_16x16x32_bf16 v[52:55], v[208:211], v[176:179], v[52:55]
	v_mfma_f32_16x16x32_bf16 v[48:51], v[216:219], v[176:179], v[48:51]
	v_mfma_f32_16x16x32_bf16 v[36:39], v[208:211], v[184:187], v[36:39]
	v_mfma_f32_16x16x32_bf16 v[32:35], v[216:219], v[184:187], v[32:35]
	v_mfma_f32_16x16x32_bf16 v[12:15], v[208:211], v[192:195], v[12:15]
	v_mfma_f32_16x16x32_bf16 v[8:11], v[216:219], v[192:195], v[8:11]
	v_mfma_f32_16x16x32_bf16 v[4:7], v[208:211], v[200:203], v[4:7]
	v_mfma_f32_16x16x32_bf16 v[0:3], v[216:219], v[200:203], v[0:3]
	s_setprio 0
	s_add_i32 s60, s60, 2
	s_add_u32 s2, s2, 0x100
	s_addc_u32 s3, s3, 0
	s_add_u32 s58, s58, 0x100
	s_addc_u32 s59, s59, 0
	s_cmp_gt_u32 s60, 61
	s_barrier
	s_cbranch_scc0 .LBB0_1515
	v_add_u32_e32 v152, s50, v162
	v_readlane_b32 s72, v243, 21
	v_add_u32_e32 v190, s57, v164
	ds_read_b128 v[168:171], v152
	ds_read_b128 v[104:107], v190
	ds_read_b128 v[108:111], v190 offset:16
	v_add_u32_e32 v154, s56, v160
	v_readlane_b32 s86, v243, 35
	v_readlane_b32 s87, v243, 36
	ds_read_b128 v[172:175], v152 offset:1024
	s_and_b64 s[2:3], s[26:27], exec
	s_mov_b64 s[26:27], s[86:87]
	v_or_b32_e32 v152, s28, v163
	v_or_b32_e32 v184, 16, v154
	s_cselect_b32 s2, s27, s47
	s_cselect_b32 s3, s26, s46
	v_ashrrev_i32_e32 v153, 31, v152
	v_ashrrev_i32_e32 v185, 31, v184
	s_waitcnt lgkmcnt(0)
	v_lshlrev_b32_e32 v176, 16, v168
	v_and_b32_e32 v177, 0xffff0000, v168
	v_lshlrev_b32_e32 v178, 16, v169
	v_and_b32_e32 v179, 0xffff0000, v169
	v_lshl_add_u64 v[156:157], v[152:153], 1, s[24:25]
	v_lshlrev_b64 v[168:169], 11, v[184:185]
	v_mov_b32_e32 v188, s3
	v_mov_b32_e32 v189, s2
	v_ashrrev_i32_e32 v155, 31, v154
	v_lshlrev_b32_e32 v180, 16, v170
	v_and_b32_e32 v181, 0xffff0000, v170
	v_lshlrev_b32_e32 v182, 16, v171
	v_and_b32_e32 v183, 0xffff0000, v171
	v_lshl_add_u64 v[186:187], v[156:157], 0, v[168:169]
	v_lshl_add_u64 v[152:153], v[152:153], 2, v[188:189]
	v_lshlrev_b64 v[188:189], 12, v[154:155]
	v_pk_fma_f32 v[134:135], v[134:135], v[106:107], v[178:179]
	v_pk_fma_f32 v[132:133], v[132:133], v[104:105], v[176:177]
	global_load_dwordx4 v[168:171], v[186:187], off
	v_lshl_add_u64 v[188:189], v[152:153], 0, v[188:189]
	v_pk_add_f32 v[134:135], v[134:135], 0 op_sel_hi:[1,0]
	v_pk_add_f32 v[132:133], v[132:133], 0 op_sel_hi:[1,0]
	v_pk_fma_f32 v[130:131], v[130:131], v[110:111], v[182:183]
	v_pk_fma_f32 v[128:129], v[128:129], v[108:109], v[180:181]
	v_pk_add_f32 v[130:131], v[130:131], 0 op_sel_hi:[1,0]
	v_pk_add_f32 v[128:129], v[128:129], 0 op_sel_hi:[1,0]
	global_store_dwordx4 v[188:189], v[132:135], off
	global_store_dwordx4 v[188:189], v[128:131], off offset:16
	global_load_dwordx4 v[176:179], v[186:187], off offset:256
	s_mov_b32 s98, 0x8000
	s_mov_b32 s99, 0
	s_mov_b32 s100, 0x28000
	s_mov_b32 s101, 0
	v_lshl_add_u64 v[248:249], v[186:187], 0, s[98:99]
	global_load_dwordx4 v[244:247], v[248:249], off
	global_load_dwordx4 v[244:247], v[248:249], off offset:256
	v_lshl_add_u64 v[248:249], v[248:249], 0, s[98:99]
	global_load_dwordx4 v[244:247], v[248:249], off
	global_load_dwordx4 v[244:247], v[248:249], off offset:256
	v_lshl_add_u64 v[248:249], v[248:249], 0, s[100:101]
	global_load_dwordx4 v[244:247], v[248:249], off
	global_load_dwordx4 v[244:247], v[248:249], off offset:256
	v_lshl_add_u64 v[248:249], v[248:249], 0, s[98:99]
	global_load_dwordx4 v[244:247], v[248:249], off
	global_load_dwordx4 v[244:247], v[248:249], off offset:256
	v_lshl_add_u64 v[248:249], v[248:249], 0, s[98:99]
	global_load_dwordx4 v[244:247], v[248:249], off
	global_load_dwordx4 v[244:247], v[248:249], off offset:256
	v_lshl_add_u64 v[248:249], v[248:249], 0, s[98:99]
	global_load_dwordx4 v[244:247], v[248:249], off
	global_load_dwordx4 v[244:247], v[248:249], off offset:256
	ds_read_b128 v[128:131], v190 offset:512
	ds_read_b128 v[132:135], v190 offset:528
	v_lshlrev_b32_e32 v186, 16, v172
	v_and_b32_e32 v187, 0xffff0000, v172
	v_lshlrev_b32_e32 v172, 16, v173
	v_and_b32_e32 v173, 0xffff0000, v173
	v_lshlrev_b32_e32 v190, 16, v174
	v_and_b32_e32 v191, 0xffff0000, v174
	v_lshlrev_b32_e32 v174, 16, v175
	v_and_b32_e32 v175, 0xffff0000, v175
	v_or_b32_e32 v180, 32, v154
	s_waitcnt lgkmcnt(0)
	v_pk_fma_f32 v[126:127], v[126:127], v[130:131], v[172:173]
	v_pk_fma_f32 v[124:125], v[124:125], v[128:129], v[186:187]
	v_pk_fma_f32 v[172:173], v[122:123], v[134:135], v[174:175]
	v_pk_fma_f32 v[174:175], v[120:121], v[132:133], v[190:191]
	v_ashrrev_i32_e32 v181, 31, v180
	v_pk_add_f32 v[122:123], v[126:127], 0 op_sel_hi:[1,0]
	v_pk_add_f32 v[120:121], v[124:125], 0 op_sel_hi:[1,0]
	v_pk_add_f32 v[126:127], v[172:173], 0 op_sel_hi:[1,0]
	v_pk_add_f32 v[124:125], v[174:175], 0 op_sel_hi:[1,0]
	v_lshlrev_b64 v[182:183], 12, v[184:185]
	v_lshlrev_b64 v[184:185], 11, v[180:181]
	global_store_dwordx4 v[188:189], v[120:123], off offset:512
	global_store_dwordx4 v[188:189], v[124:127], off offset:528
	v_lshl_add_u64 v[184:185], v[156:157], 0, v[184:185]
	v_lshl_add_u64 v[182:183], v[152:153], 0, v[182:183]
	global_load_dwordx4 v[120:123], v[184:185], off
	s_mov_b32 s19, s16
	s_mov_b32 s36, s18
	s_mov_b64 s[30:31], s[22:23]
	s_mov_b64 s[34:35], s[20:21]
	s_mov_b32 s20, s55
	s_and_b64 vcc, exec, s[0:1]
	v_readlane_b32 s73, v243, 22
	v_readlane_b32 s74, v243, 23
	v_readlane_b32 s75, v243, 24
	v_readlane_b32 s76, v243, 25
	v_readlane_b32 s77, v243, 26
	v_readlane_b32 s78, v243, 27
	v_readlane_b32 s79, v243, 28
	v_readlane_b32 s80, v243, 29
	v_readlane_b32 s81, v243, 30
	v_readlane_b32 s82, v243, 31
	v_readlane_b32 s83, v243, 32
	v_readlane_b32 s84, v243, 33
	v_readlane_b32 s85, v243, 34
	s_waitcnt vmcnt(0)
	v_lshlrev_b32_e32 v124, 16, v168
	v_and_b32_e32 v125, 0xffff0000, v168
	v_lshlrev_b32_e32 v126, 16, v169
	v_and_b32_e32 v127, 0xffff0000, v169
	v_lshlrev_b32_e32 v168, 16, v170
	v_and_b32_e32 v169, 0xffff0000, v170
	v_lshlrev_b32_e32 v170, 16, v171
	v_and_b32_e32 v171, 0xffff0000, v171
	v_pk_fma_f32 v[116:117], v[116:117], v[104:105], v[124:125]
	v_pk_fma_f32 v[118:119], v[118:119], v[106:107], v[126:127]
	v_pk_fma_f32 v[124:125], v[112:113], v[108:109], v[168:169]
	v_pk_fma_f32 v[126:127], v[114:115], v[110:111], v[170:171]
	v_pk_add_f32 v[114:115], v[118:119], 0 op_sel_hi:[1,0]
	v_pk_add_f32 v[112:113], v[116:117], 0 op_sel_hi:[1,0]
	v_pk_add_f32 v[118:119], v[126:127], 0 op_sel_hi:[1,0]
	v_pk_add_f32 v[116:117], v[124:125], 0 op_sel_hi:[1,0]
	v_lshlrev_b32_e32 v124, 16, v176
	v_and_b32_e32 v125, 0xffff0000, v176
	v_lshlrev_b32_e32 v126, 16, v177
	v_and_b32_e32 v127, 0xffff0000, v177
	global_store_dwordx4 v[182:183], v[116:119], off offset:16
	v_pk_fma_f32 v[100:101], v[100:101], v[128:129], v[124:125]
	v_pk_fma_f32 v[102:103], v[102:103], v[130:131], v[126:127]
	v_lshlrev_b32_e32 v116, 16, v178
	v_and_b32_e32 v117, 0xffff0000, v178
	v_lshlrev_b32_e32 v118, 16, v179
	v_and_b32_e32 v119, 0xffff0000, v179
	global_store_dwordx4 v[182:183], v[112:115], off
	v_pk_add_f32 v[102:103], v[102:103], 0 op_sel_hi:[1,0]
	v_pk_add_f32 v[100:101], v[100:101], 0 op_sel_hi:[1,0]
	v_pk_fma_f32 v[96:97], v[96:97], v[132:133], v[116:117]
	v_pk_fma_f32 v[98:99], v[98:99], v[134:135], v[118:119]
	global_load_dwordx4 v[112:115], v[184:185], off offset:256
	v_pk_add_f32 v[98:99], v[98:99], 0 op_sel_hi:[1,0]
	v_pk_add_f32 v[96:97], v[96:97], 0 op_sel_hi:[1,0]
	global_store_dwordx4 v[182:183], v[100:103], off offset:512
	global_store_dwordx4 v[182:183], v[96:99], off offset:528
	v_lshlrev_b32_e32 v126, 16, v120
	v_or_b32_e32 v100, 48, v154
	v_ashrrev_i32_e32 v101, 31, v100
	v_lshlrev_b64 v[96:97], 11, v[100:101]
	v_lshl_add_u64 v[102:103], v[156:157], 0, v[96:97]
	global_load_dwordx4 v[96:99], v[102:103], off
	v_and_b32_e32 v127, 0xffff0000, v120
	v_lshlrev_b32_e32 v120, 16, v121
	v_and_b32_e32 v121, 0xffff0000, v121
	v_lshlrev_b64 v[118:119], 12, v[180:181]
	v_lshlrev_b32_e32 v168, 16, v122
	v_and_b32_e32 v169, 0xffff0000, v122
	v_lshlrev_b32_e32 v122, 16, v123
	v_and_b32_e32 v123, 0xffff0000, v123
	v_pk_fma_f32 v[92:93], v[92:93], v[104:105], v[126:127]
	v_pk_fma_f32 v[94:95], v[94:95], v[106:107], v[120:121]
	v_lshl_add_u64 v[118:119], v[152:153], 0, v[118:119]
	v_pk_fma_f32 v[120:121], v[88:89], v[108:109], v[168:169]
	v_pk_fma_f32 v[122:123], v[90:91], v[110:111], v[122:123]
	v_pk_add_f32 v[90:91], v[94:95], 0 op_sel_hi:[1,0]
	v_pk_add_f32 v[88:89], v[92:93], 0 op_sel_hi:[1,0]
	v_pk_add_f32 v[94:95], v[122:123], 0 op_sel_hi:[1,0]
	v_pk_add_f32 v[92:93], v[120:121], 0 op_sel_hi:[1,0]
	global_store_dwordx4 v[118:119], v[88:91], off
	global_store_dwordx4 v[118:119], v[92:95], off offset:16
	v_add_u32_e32 v116, 0x80, v154
	global_load_dwordx4 v[88:91], v[102:103], off offset:256
	v_ashrrev_i32_e32 v117, 31, v116
	v_lshlrev_b64 v[124:125], 11, v[116:117]
	v_lshl_add_u64 v[124:125], v[156:157], 0, v[124:125]
	v_lshlrev_b64 v[100:101], 12, v[100:101]
	v_lshl_add_u64 v[100:101], v[152:153], 0, v[100:101]
	s_waitcnt vmcnt(6)
	v_lshlrev_b32_e32 v92, 16, v112
	v_and_b32_e32 v93, 0xffff0000, v112
	v_lshlrev_b32_e32 v94, 16, v113
	v_and_b32_e32 v95, 0xffff0000, v113
	v_lshlrev_b32_e32 v102, 16, v114
	v_and_b32_e32 v103, 0xffff0000, v114
	v_lshlrev_b32_e32 v112, 16, v115
	v_and_b32_e32 v113, 0xffff0000, v115
	v_pk_fma_f32 v[84:85], v[84:85], v[128:129], v[92:93]
	v_pk_fma_f32 v[86:87], v[86:87], v[130:131], v[94:95]
	v_pk_fma_f32 v[92:93], v[80:81], v[132:133], v[102:103]
	v_pk_fma_f32 v[94:95], v[82:83], v[134:135], v[112:113]
	v_pk_add_f32 v[82:83], v[86:87], 0 op_sel_hi:[1,0]
	v_pk_add_f32 v[80:81], v[84:85], 0 op_sel_hi:[1,0]
	v_pk_add_f32 v[86:87], v[94:95], 0 op_sel_hi:[1,0]
	v_pk_add_f32 v[84:85], v[92:93], 0 op_sel_hi:[1,0]
	global_store_dwordx4 v[118:119], v[80:83], off offset:512
	global_store_dwordx4 v[118:119], v[84:87], off offset:528
	global_load_dwordx4 v[80:83], v[124:125], off
	s_waitcnt vmcnt(6)
	v_lshlrev_b32_e32 v92, 16, v98
	v_lshlrev_b32_e32 v84, 16, v96
	v_and_b32_e32 v85, 0xffff0000, v96
	v_lshlrev_b32_e32 v86, 16, v97
	v_and_b32_e32 v87, 0xffff0000, v97
	v_and_b32_e32 v93, 0xffff0000, v98
	v_lshlrev_b32_e32 v94, 16, v99
	v_and_b32_e32 v95, 0xffff0000, v99
	v_pk_fma_f32 v[76:77], v[76:77], v[104:105], v[84:85]
	v_pk_fma_f32 v[78:79], v[78:79], v[106:107], v[86:87]
	v_pk_fma_f32 v[84:85], v[72:73], v[108:109], v[92:93]
	v_pk_fma_f32 v[86:87], v[74:75], v[110:111], v[94:95]
	v_pk_add_f32 v[74:75], v[78:79], 0 op_sel_hi:[1,0]
	v_pk_add_f32 v[72:73], v[76:77], 0 op_sel_hi:[1,0]
	v_pk_add_f32 v[78:79], v[86:87], 0 op_sel_hi:[1,0]
	v_pk_add_f32 v[76:77], v[84:85], 0 op_sel_hi:[1,0]
	global_store_dwordx4 v[100:101], v[72:75], off
	global_store_dwordx4 v[100:101], v[76:79], off offset:16
	global_load_dwordx4 v[72:75], v[124:125], off offset:256
	s_waitcnt vmcnt(6)
	v_lshlrev_b32_e32 v94, 16, v88
	v_add_u32_e32 v76, 0x90, v154
	v_and_b32_e32 v95, 0xffff0000, v88
	v_lshlrev_b32_e32 v88, 16, v89
	v_and_b32_e32 v89, 0xffff0000, v89
	v_lshlrev_b32_e32 v96, 16, v90
	v_and_b32_e32 v97, 0xffff0000, v90
	v_lshlrev_b32_e32 v90, 16, v91
	v_and_b32_e32 v91, 0xffff0000, v91
	v_ashrrev_i32_e32 v77, 31, v76
	v_pk_fma_f32 v[68:69], v[68:69], v[128:129], v[94:95]
	v_pk_fma_f32 v[70:71], v[70:71], v[130:131], v[88:89]
	v_pk_fma_f32 v[88:89], v[64:65], v[132:133], v[96:97]
	v_pk_fma_f32 v[90:91], v[66:67], v[134:135], v[90:91]
	v_lshlrev_b64 v[86:87], 11, v[76:77]
	v_pk_add_f32 v[66:67], v[70:71], 0 op_sel_hi:[1,0]
	v_pk_add_f32 v[64:65], v[68:69], 0 op_sel_hi:[1,0]
	v_pk_add_f32 v[70:71], v[90:91], 0 op_sel_hi:[1,0]
	v_pk_add_f32 v[68:69], v[88:89], 0 op_sel_hi:[1,0]
	v_lshl_add_u64 v[86:87], v[156:157], 0, v[86:87]
	global_store_dwordx4 v[100:101], v[64:67], off offset:512
	global_store_dwordx4 v[100:101], v[68:71], off offset:528
	v_lshlrev_b64 v[84:85], 12, v[116:117]
	global_load_dwordx4 v[64:67], v[86:87], off
	v_lshl_add_u64 v[84:85], v[152:153], 0, v[84:85]
	v_add_u32_e32 v78, 0xa0, v154
	v_ashrrev_i32_e32 v79, 31, v78
	v_lshlrev_b64 v[92:93], 11, v[78:79]
	v_lshl_add_u64 v[92:93], v[156:157], 0, v[92:93]
	s_waitcnt vmcnt(6)
	v_lshlrev_b32_e32 v68, 16, v80
	v_and_b32_e32 v69, 0xffff0000, v80
	v_lshlrev_b32_e32 v70, 16, v81
	v_and_b32_e32 v71, 0xffff0000, v81
	v_lshlrev_b32_e32 v80, 16, v82
	v_and_b32_e32 v81, 0xffff0000, v82
	v_lshlrev_b32_e32 v82, 16, v83
	v_and_b32_e32 v83, 0xffff0000, v83
	v_pk_fma_f32 v[60:61], v[60:61], v[104:105], v[68:69]
	v_pk_fma_f32 v[62:63], v[62:63], v[106:107], v[70:71]
	v_pk_fma_f32 v[68:69], v[56:57], v[108:109], v[80:81]
	v_pk_fma_f32 v[70:71], v[58:59], v[110:111], v[82:83]
	v_pk_add_f32 v[58:59], v[62:63], 0 op_sel_hi:[1,0]
	v_pk_add_f32 v[56:57], v[60:61], 0 op_sel_hi:[1,0]
	v_pk_add_f32 v[62:63], v[70:71], 0 op_sel_hi:[1,0]
	v_pk_add_f32 v[60:61], v[68:69], 0 op_sel_hi:[1,0]
	global_store_dwordx4 v[84:85], v[56:59], off
	global_store_dwordx4 v[84:85], v[60:63], off offset:16
	global_load_dwordx4 v[56:59], v[86:87], off offset:256
	s_waitcnt vmcnt(6)
	v_lshlrev_b32_e32 v68, 16, v74
	v_lshlrev_b32_e32 v60, 16, v72
	v_and_b32_e32 v61, 0xffff0000, v72
	v_lshlrev_b32_e32 v62, 16, v73
	v_and_b32_e32 v63, 0xffff0000, v73
	v_and_b32_e32 v69, 0xffff0000, v74
	v_lshlrev_b32_e32 v70, 16, v75
	v_and_b32_e32 v71, 0xffff0000, v75
	v_pk_fma_f32 v[52:53], v[52:53], v[128:129], v[60:61]
	v_pk_fma_f32 v[54:55], v[54:55], v[130:131], v[62:63]
	v_pk_fma_f32 v[60:61], v[48:49], v[132:133], v[68:69]
	v_pk_fma_f32 v[62:63], v[50:51], v[134:135], v[70:71]
	v_pk_add_f32 v[50:51], v[54:55], 0 op_sel_hi:[1,0]
	v_pk_add_f32 v[48:49], v[52:53], 0 op_sel_hi:[1,0]
	v_pk_add_f32 v[54:55], v[62:63], 0 op_sel_hi:[1,0]
	v_pk_add_f32 v[52:53], v[60:61], 0 op_sel_hi:[1,0]
	global_store_dwordx4 v[84:85], v[48:51], off offset:512
	global_store_dwordx4 v[84:85], v[52:55], off offset:528
	global_load_dwordx4 v[48:51], v[92:93], off
	v_lshlrev_b64 v[60:61], 12, v[78:79]
	v_lshlrev_b64 v[54:55], 12, v[76:77]
	v_lshl_add_u64 v[54:55], v[152:153], 0, v[54:55]
	v_add_u32_e32 v52, 0xb0, v154
	v_ashrrev_i32_e32 v53, 31, v52
	s_waitcnt vmcnt(6)
	v_lshlrev_b32_e32 v68, 16, v64
	v_and_b32_e32 v69, 0xffff0000, v64
	v_lshlrev_b32_e32 v64, 16, v65
	v_and_b32_e32 v65, 0xffff0000, v65
	v_lshlrev_b32_e32 v70, 16, v66
	v_and_b32_e32 v71, 0xffff0000, v66
	v_lshlrev_b32_e32 v66, 16, v67
	v_and_b32_e32 v67, 0xffff0000, v67
	v_pk_fma_f32 v[44:45], v[44:45], v[104:105], v[68:69]
	v_pk_fma_f32 v[46:47], v[46:47], v[106:107], v[64:65]
	v_pk_fma_f32 v[64:65], v[40:41], v[108:109], v[70:71]
	v_pk_fma_f32 v[66:67], v[42:43], v[110:111], v[66:67]
	v_pk_add_f32 v[42:43], v[46:47], 0 op_sel_hi:[1,0]
	v_pk_add_f32 v[40:41], v[44:45], 0 op_sel_hi:[1,0]
	v_pk_add_f32 v[46:47], v[66:67], 0 op_sel_hi:[1,0]
	v_pk_add_f32 v[44:45], v[64:65], 0 op_sel_hi:[1,0]
	global_store_dwordx4 v[54:55], v[40:43], off
	global_store_dwordx4 v[54:55], v[44:47], off offset:16
	global_load_dwordx4 v[40:43], v[92:93], off offset:256
	v_lshlrev_b64 v[62:63], 11, v[52:53]
	v_lshl_add_u64 v[62:63], v[156:157], 0, v[62:63]
	v_lshl_add_u64 v[60:61], v[152:153], 0, v[60:61]
	s_waitcnt vmcnt(6)
	v_lshlrev_b32_e32 v44, 16, v56
	v_and_b32_e32 v45, 0xffff0000, v56
	v_lshlrev_b32_e32 v46, 16, v57
	v_and_b32_e32 v47, 0xffff0000, v57
	v_lshlrev_b32_e32 v56, 16, v58
	v_and_b32_e32 v57, 0xffff0000, v58
	v_lshlrev_b32_e32 v58, 16, v59
	v_and_b32_e32 v59, 0xffff0000, v59
	v_pk_fma_f32 v[36:37], v[36:37], v[128:129], v[44:45]
	v_pk_fma_f32 v[38:39], v[38:39], v[130:131], v[46:47]
	v_pk_fma_f32 v[44:45], v[32:33], v[132:133], v[56:57]
	v_pk_fma_f32 v[46:47], v[34:35], v[134:135], v[58:59]
	v_pk_add_f32 v[34:35], v[38:39], 0 op_sel_hi:[1,0]
	v_pk_add_f32 v[32:33], v[36:37], 0 op_sel_hi:[1,0]
	v_pk_add_f32 v[38:39], v[46:47], 0 op_sel_hi:[1,0]
	v_pk_add_f32 v[36:37], v[44:45], 0 op_sel_hi:[1,0]
	global_store_dwordx4 v[54:55], v[32:35], off offset:512
	global_store_dwordx4 v[54:55], v[36:39], off offset:528
	global_load_dwordx4 v[32:35], v[62:63], off
	s_waitcnt vmcnt(6)
	v_lshlrev_b32_e32 v44, 16, v50
	v_lshlrev_b32_e32 v36, 16, v48
	v_and_b32_e32 v37, 0xffff0000, v48
	v_lshlrev_b32_e32 v38, 16, v49
	v_and_b32_e32 v39, 0xffff0000, v49
	v_and_b32_e32 v45, 0xffff0000, v50
	v_lshlrev_b32_e32 v46, 16, v51
	v_and_b32_e32 v47, 0xffff0000, v51
	v_pk_fma_f32 v[28:29], v[28:29], v[104:105], v[36:37]
	v_pk_fma_f32 v[30:31], v[30:31], v[106:107], v[38:39]
	v_pk_fma_f32 v[36:37], v[24:25], v[108:109], v[44:45]
	v_pk_fma_f32 v[38:39], v[26:27], v[110:111], v[46:47]
	v_pk_add_f32 v[26:27], v[30:31], 0 op_sel_hi:[1,0]
	v_pk_add_f32 v[24:25], v[28:29], 0 op_sel_hi:[1,0]
	v_pk_add_f32 v[30:31], v[38:39], 0 op_sel_hi:[1,0]
	v_pk_add_f32 v[28:29], v[36:37], 0 op_sel_hi:[1,0]
	global_store_dwordx4 v[60:61], v[24:27], off
	global_store_dwordx4 v[60:61], v[28:31], off offset:16
	global_load_dwordx4 v[24:27], v[62:63], off offset:256
	s_waitcnt vmcnt(6)
	v_lshlrev_b32_e32 v36, 16, v41
	v_lshlrev_b32_e32 v30, 16, v40
	v_and_b32_e32 v31, 0xffff0000, v40
	v_and_b32_e32 v37, 0xffff0000, v41
	v_lshlrev_b32_e32 v38, 16, v42
	v_and_b32_e32 v39, 0xffff0000, v42
	v_lshlrev_b32_e32 v40, 16, v43
	v_and_b32_e32 v41, 0xffff0000, v43
	v_pk_fma_f32 v[12:13], v[12:13], v[128:129], v[30:31]
	v_pk_fma_f32 v[14:15], v[14:15], v[130:131], v[36:37]
	v_pk_fma_f32 v[30:31], v[8:9], v[132:133], v[38:39]
	v_pk_fma_f32 v[36:37], v[10:11], v[134:135], v[40:41]
	v_pk_add_f32 v[10:11], v[14:15], 0 op_sel_hi:[1,0]
	v_pk_add_f32 v[8:9], v[12:13], 0 op_sel_hi:[1,0]
	v_pk_add_f32 v[14:15], v[36:37], 0 op_sel_hi:[1,0]
	v_pk_add_f32 v[12:13], v[30:31], 0 op_sel_hi:[1,0]
	global_store_dwordx4 v[60:61], v[8:11], off offset:512
	global_store_dwordx4 v[60:61], v[12:15], off offset:528
	v_lshlrev_b64 v[28:29], 12, v[52:53]
	v_lshl_add_u64 v[28:29], v[152:153], 0, v[28:29]
	s_waitcnt vmcnt(5)
	v_lshlrev_b32_e32 v8, 16, v32
	v_and_b32_e32 v9, 0xffff0000, v32
	v_lshlrev_b32_e32 v10, 16, v33
	v_and_b32_e32 v11, 0xffff0000, v33
	v_lshlrev_b32_e32 v12, 16, v34
	v_and_b32_e32 v13, 0xffff0000, v34
	v_lshlrev_b32_e32 v14, 16, v35
	v_and_b32_e32 v15, 0xffff0000, v35
	v_pk_fma_f32 v[12:13], v[16:17], v[108:109], v[12:13]
	v_pk_fma_f32 v[14:15], v[18:19], v[110:111], v[14:15]
	v_pk_fma_f32 v[16:17], v[20:21], v[104:105], v[8:9]
	v_pk_fma_f32 v[18:19], v[22:23], v[106:107], v[10:11]
	v_pk_add_f32 v[10:11], v[14:15], 0 op_sel_hi:[1,0]
	v_pk_add_f32 v[8:9], v[12:13], 0 op_sel_hi:[1,0]
	v_pk_add_f32 v[14:15], v[18:19], 0 op_sel_hi:[1,0]
	v_pk_add_f32 v[12:13], v[16:17], 0 op_sel_hi:[1,0]
	global_store_dwordx4 v[28:29], v[12:15], off
	global_store_dwordx4 v[28:29], v[8:11], off offset:16
	s_waitcnt vmcnt(4)
	v_lshlrev_b32_e32 v12, 16, v24
	v_and_b32_e32 v13, 0xffff0000, v24
	v_lshlrev_b32_e32 v14, 16, v25
	v_and_b32_e32 v15, 0xffff0000, v25
	v_lshlrev_b32_e32 v8, 16, v26
	v_and_b32_e32 v9, 0xffff0000, v26
	v_lshlrev_b32_e32 v10, 16, v27
	v_and_b32_e32 v11, 0xffff0000, v27
	v_pk_fma_f32 v[4:5], v[4:5], v[128:129], v[12:13]
	v_pk_fma_f32 v[6:7], v[6:7], v[130:131], v[14:15]
	v_pk_fma_f32 v[0:1], v[0:1], v[132:133], v[8:9]
	v_pk_fma_f32 v[2:3], v[2:3], v[134:135], v[10:11]
	v_pk_add_f32 v[6:7], v[6:7], 0 op_sel_hi:[1,0]
	v_pk_add_f32 v[4:5], v[4:5], 0 op_sel_hi:[1,0]
	v_pk_add_f32 v[2:3], v[2:3], 0 op_sel_hi:[1,0]
	v_pk_add_f32 v[0:1], v[0:1], 0 op_sel_hi:[1,0]
	global_store_dwordx4 v[28:29], v[4:7], off offset:512
	global_store_dwordx4 v[28:29], v[0:3], off offset:528
	s_cbranch_vccz .LBB0_1505
	s_waitcnt vmcnt(0)
	s_cmpk_gt_u32 s33, 0xff
	s_cbranch_scc1 .LBB0_1519
	s_barrier

	.amdhsa_kernel _Z14fwd_megakernel1P
		.amdhsa_group_segment_fixed_size 0
		.amdhsa_private_segment_fixed_size 0
		.amdhsa_kernarg_size 520
		.amdhsa_user_sgpr_count 2
		.amdhsa_user_sgpr_dispatch_ptr 0
		.amdhsa_user_sgpr_queue_ptr 0
		.amdhsa_user_sgpr_kernarg_segment_ptr 1
		.amdhsa_user_sgpr_dispatch_id 0
		.amdhsa_user_sgpr_kernarg_preload_length 0
		.amdhsa_user_sgpr_kernarg_preload_offset 0
		.amdhsa_user_sgpr_private_segment_size 0
		.amdhsa_uses_dynamic_stack 0
		.amdhsa_enable_private_segment 0
		.amdhsa_system_sgpr_workgroup_id_x 1
		.amdhsa_system_sgpr_workgroup_id_y 0
		.amdhsa_system_sgpr_workgroup_id_z 0
		.amdhsa_system_sgpr_workgroup_info 0
		.amdhsa_system_vgpr_workitem_id 2
		.amdhsa_next_free_vgpr 256
		.amdhsa_next_free_sgpr 102
		.amdhsa_accum_offset 256
		.amdhsa_reserve_vcc 1
		.amdhsa_float_round_mode_32 0
		.amdhsa_float_round_mode_16_64 0
		.amdhsa_float_denorm_mode_32 3
		.amdhsa_float_denorm_mode_16_64 3
		.amdhsa_dx10_clamp 1
		.amdhsa_ieee_mode 1
		.amdhsa_fp16_overflow 0
		.amdhsa_tg_split 0
		.amdhsa_exception_fp_ieee_invalid_op 0
		.amdhsa_exception_fp_denorm_src 0
		.amdhsa_exception_fp_ieee_div_zero 0
		.amdhsa_exception_fp_ieee_overflow 0
		.amdhsa_exception_fp_ieee_underflow 0
		.amdhsa_exception_fp_ieee_inexact 0
		.amdhsa_exception_int_div_zero 0
	.end_amdhsa_kernel

amdhsa.kernels:
  - .agpr_count:     0
    .args:
      - .offset:         0
        .size:           264
        .value_kind:     by_value
      - .offset:         264
        .size:           4
        .value_kind:     hidden_block_count_x
      - .offset:         268
        .size:           4
        .value_kind:     hidden_block_count_y
      - .offset:         272
        .size:           4
        .value_kind:     hidden_block_count_z
      - .offset:         276
        .size:           2
        .value_kind:     hidden_group_size_x
      - .offset:         278
        .size:           2
        .value_kind:     hidden_group_size_y
      - .offset:         280
        .size:           2
        .value_kind:     hidden_group_size_z
      - .offset:         282
        .size:           2
        .value_kind:     hidden_remainder_x
      - .offset:         284
        .size:           2
        .value_kind:     hidden_remainder_y
      - .offset:         286
        .size:           2
        .value_kind:     hidden_remainder_z
      - .offset:         304
        .size:           8
        .value_kind:     hidden_global_offset_x
      - .offset:         312
        .size:           8
        .value_kind:     hidden_global_offset_y
      - .offset:         320
        .size:           8
        .value_kind:     hidden_global_offset_z
      - .offset:         328
        .size:           2
        .value_kind:     hidden_grid_dims
      - .offset:         352
        .size:           8
        .value_kind:     hidden_multigrid_sync_arg
      - .offset:         384
        .size:           4
        .value_kind:     hidden_dynamic_lds_size
    .group_segment_fixed_size: 0
    .kernarg_segment_align: 8
    .kernarg_segment_size: 520
    .language:       OpenCL C
    .language_version:
      - 2
      - 0
    .max_flat_workgroup_size: 512
    .name:           _Z14fwd_megakernel1P
    .private_segment_fixed_size: 0
    .sgpr_count:     108
    .sgpr_spill_count: 117
    .symbol:         _Z14fwd_megakernel1P.kd
    .uniform_work_group_size: 1
    .uses_dynamic_stack: false
    .vgpr_count:     256
    .vgpr_spill_count: 0
    .wavefront_size: 64
